# GEMM K-loops: vmcnt and lgkmcnt waits before each phase barrier merged into one s_waitcnt; 12 m0-hazard s_nops replaced by moving the preceding independent instruction into the slot
# speedup vs baseline: 1.0154x; 1.0011x over previous
; #define PG8_STAGE(bufoff, gbase, voff) do { unsigned long long _gb = (unsigned long long)(gbase); asm volatile("" : "+s"(_gb)); _Pragma("unroll") for (int _i = 0; _i < 2; ++_i) \
;         __builtin_amdgcn_global_load_lds((const GAS unsigned*)((const GAS char*)_gb + (voff)[_i]), (LAS unsigned*)(lds + (bufoff) + ldsw + _i * 8192), 16, 0, 0); } while (0)
; #define PG8_LDA(dst, b, h) do { _Pragma("unroll") for (int m = 0; m < 4; ++m) _Pragma("unroll") for (int k = 0; k < 2; ++k) dst[m][k] = *(const LAS bf16x8*)(lds + PG8_SA(b, h) + aoff + m * 2048 + k * 1024); } while (0)
; #define PG8_LDB(dst, b, h) do { _Pragma("unroll") for (int n = 0; n < 2; ++n) _Pragma("unroll") for (int k = 0; k < 2; ++k) dst[n][k] = *(const LAS bf16x8*)(lds + PG8_SB(b, h) + boff + n * 2048 + k * 1024); } while (0)
; #define PG8_WAIT_V(n) asm volatile("s_waitcnt vmcnt(" #n ")" ::: "memory")
; #define PG8_WAIT_L(n) asm volatile("s_waitcnt lgkmcnt(" #n ")" ::: "memory")
; #define PG8_BAR __builtin_amdgcn_s_barrier()
; #define PG8_SCHED __builtin_amdgcn_sched_barrier(0)
; template <class Epi, bool ALIGN_EPI>
; __device__ __forceinline__ void gemm_phase(LAS unsigned char* lds, const Gemm g, const StaticOrder& S, const Epi& E, const int wid) {
;     ...
;         const bool has_next = S.next(ui + 1, nxt);
;         const char* nA = has_next ? (const char*)g.A + (size_t)nxt.pm * tstep : cA; const char* nB = has_next ? (const char*)g.Bt + (size_t)nxt.pn * tstep : cB;
;         for (int t = 0; t < nt; t += 2) {
;             const bool last = (t == nt - 2);
;             const char* a1 = cA + (size_t)(t + 1) * kstep;
;             const char* a2 = last ? nA : cA + (size_t)(t + 2) * kstep; const char* b2 = last ? nB : cB + (size_t)(t + 2) * kstep;
;             const char* a3 = a2 + kstep; const char* b3 = b2 + kstep;
;             PG8_LDB(B0, 0, 0); PG8_LDB(B1, 0, 1); PG8_SCHED; PG8_LDA(At, 0, 0); PG8_STAGE(PG8_SA(1, 1), a1 + hstep, voffA);
;             PG8_WAIT_V(8); PG8_WAIT_L(0); PG8_BAR; PG8_MMA(0, 0, At, B0); PG8_MMA(0, 1, At, B1); PG8_BAR; PG8_SCHED;
;             PG8_LDA(At, 0, 1); PG8_STAGE(PG8_SB(0, 0), b2, voffB); PG8_STAGE(PG8_SB(0, 1), b2 + hstepB, voffB); PG8_STAGE(PG8_SA(0, 0), a2, voffA);
;             PG8_WAIT_V(8); PG8_WAIT_L(0); PG8_BAR; PG8_MMA(1, 0, At, B0); PG8_MMA(1, 1, At, B1); PG8_BAR; PG8_SCHED;
.LBB0_105:
	ds_read_b128 v[128:131], v204
	ds_read_b128 v[132:135], v204 offset:1024
	ds_read_b128 v[136:139], v204 offset:2048
	ds_read_b128 v[140:143], v204 offset:3072
	ds_read_b128 v[162:165], v205
	ds_read_b128 v[166:169], v205 offset:1024
	ds_read_b128 v[170:173], v205 offset:2048
	ds_read_b128 v[174:177], v205 offset:3072
	s_add_u32 s6, s2, 0x100
	s_addc_u32 s7, s3, 0
	s_cmp_eq_u32 s74, 28
	s_cselect_b32 s52, s70, s6
	s_cselect_b32 s53, s39, s7
	s_cselect_b32 s50, s71, s72
	s_cselect_b32 s51, s37, s73
	s_add_u32 s48, s52, 0x80
	s_addc_u32 s49, s53, 0
	s_add_u32 s2, s2, 0x80080
	s_addc_u32 s3, s3, 0
	ds_read_b128 v[178:181], v206
	ds_read_b128 v[186:189], v206 offset:1024
	ds_read_b128 v[190:193], v206 offset:2048
	ds_read_b128 v[194:197], v206 offset:3072
	ds_read_b128 v[198:201], v206 offset:4096
	ds_read_b128 v[210:213], v206 offset:5120
	ds_read_b128 v[214:217], v206 offset:6144
	s_add_i32 m0, s45, 0xc000
	ds_read_b128 v[218:221], v206 offset:7168
	global_load_lds_dwordx4 v144, s[2:3]
	s_add_i32 m0, s45, 0xe000
	s_nop 0
	global_load_lds_dwordx4 v148, s[2:3]
	s_waitcnt vmcnt(8) lgkmcnt(0)
	s_barrier
	s_setprio 1
	v_mfma_f32_16x16x32_bf16 v[124:127], v[128:131], v[178:181], v[124:127]
	v_mfma_f32_16x16x32_bf16 v[120:123], v[136:139], v[178:181], v[120:123]
	v_mfma_f32_16x16x32_bf16 v[108:111], v[128:131], v[190:193], v[108:111]
	v_mfma_f32_16x16x32_bf16 v[104:107], v[136:139], v[190:193], v[104:107]
	v_mfma_f32_16x16x32_bf16 v[92:95], v[128:131], v[198:201], v[92:95]
	v_mfma_f32_16x16x32_bf16 v[88:91], v[136:139], v[198:201], v[88:91]
	v_mfma_f32_16x16x32_bf16 v[76:79], v[128:131], v[214:217], v[76:79]
	v_mfma_f32_16x16x32_bf16 v[72:75], v[136:139], v[214:217], v[72:75]
	v_mfma_f32_16x16x32_bf16 v[124:127], v[132:135], v[186:189], v[124:127]
	v_mfma_f32_16x16x32_bf16 v[120:123], v[140:143], v[186:189], v[120:123]
	v_mfma_f32_16x16x32_bf16 v[108:111], v[132:135], v[194:197], v[108:111]
	v_mfma_f32_16x16x32_bf16 v[104:107], v[140:143], v[194:197], v[104:107]
	v_mfma_f32_16x16x32_bf16 v[92:95], v[132:135], v[210:213], v[92:95]
	v_mfma_f32_16x16x32_bf16 v[88:91], v[140:143], v[210:213], v[88:91]
	v_mfma_f32_16x16x32_bf16 v[76:79], v[132:135], v[218:221], v[76:79]
	v_mfma_f32_16x16x32_bf16 v[72:75], v[140:143], v[218:221], v[72:75]
	v_mfma_f32_16x16x32_bf16 v[116:119], v[162:165], v[178:181], v[116:119]
	v_mfma_f32_16x16x32_bf16 v[112:115], v[170:173], v[178:181], v[112:115]
	v_mfma_f32_16x16x32_bf16 v[100:103], v[162:165], v[190:193], v[100:103]
	v_mfma_f32_16x16x32_bf16 v[96:99], v[170:173], v[190:193], v[96:99]
	v_mfma_f32_16x16x32_bf16 v[84:87], v[162:165], v[198:201], v[84:87]
	v_mfma_f32_16x16x32_bf16 v[80:83], v[170:173], v[198:201], v[80:83]
	v_mfma_f32_16x16x32_bf16 v[68:71], v[162:165], v[214:217], v[68:71]
	v_mfma_f32_16x16x32_bf16 v[64:67], v[170:173], v[214:217], v[64:67]
	v_mfma_f32_16x16x32_bf16 v[116:119], v[166:169], v[186:189], v[116:119]
	v_mfma_f32_16x16x32_bf16 v[112:115], v[174:177], v[186:189], v[112:115]
	v_mfma_f32_16x16x32_bf16 v[100:103], v[166:169], v[194:197], v[100:103]
	v_mfma_f32_16x16x32_bf16 v[96:99], v[174:177], v[194:197], v[96:99]
	v_mfma_f32_16x16x32_bf16 v[84:87], v[166:169], v[210:213], v[84:87]
	v_mfma_f32_16x16x32_bf16 v[80:83], v[174:177], v[210:213], v[80:83]
	v_mfma_f32_16x16x32_bf16 v[68:71], v[166:169], v[218:221], v[68:71]
	v_mfma_f32_16x16x32_bf16 v[64:67], v[174:177], v[218:221], v[64:67]
	s_setprio 0
	s_barrier
	s_mov_b64 s[2:3], s[50:51]
	s_add_i32 s75, s66, s33
	ds_read_b128 v[178:181], v206 offset:16384
	ds_read_b128 v[186:189], v206 offset:17408
	ds_read_b128 v[190:193], v206 offset:18432
	ds_read_b128 v[194:197], v206 offset:19456
	ds_read_b128 v[198:201], v206 offset:20480
	ds_read_b128 v[210:213], v206 offset:21504
	ds_read_b128 v[214:217], v206 offset:22528
	s_mov_b32 m0, s75
	ds_read_b128 v[218:221], v206 offset:23552
	global_load_lds_dwordx4 v146, s[2:3]
	s_add_i32 m0, s75, 0x2000
	s_nop 0
	global_load_lds_dwordx4 v150, s[2:3]
	s_add_u32 s2, s50, 0x20000
	s_addc_u32 s3, s51, 0
	s_add_i32 s75, s67, s33
	s_mov_b32 m0, s75
	s_nop 0
	global_load_lds_dwordx4 v146, s[2:3]
	s_add_i32 m0, s75, 0x2000
	s_nop 0
	global_load_lds_dwordx4 v150, s[2:3]
	s_mov_b32 m0, s45
	s_mov_b64 s[2:3], s[52:53]
	global_load_lds_dwordx4 v144, s[2:3]
	s_mov_b32 m0, s47
	s_nop 0
	global_load_lds_dwordx4 v148, s[2:3]
	s_waitcnt vmcnt(8) lgkmcnt(0)
	s_barrier
	s_setprio 1
	v_mfma_f32_16x16x32_bf16 v[60:63], v[128:131], v[178:181], v[60:63]
	v_mfma_f32_16x16x32_bf16 v[56:59], v[136:139], v[178:181], v[56:59]
	v_mfma_f32_16x16x32_bf16 v[44:47], v[128:131], v[190:193], v[44:47]
	v_mfma_f32_16x16x32_bf16 v[40:43], v[136:139], v[190:193], v[40:43]
	v_mfma_f32_16x16x32_bf16 v[28:31], v[128:131], v[198:201], v[28:31]
	v_mfma_f32_16x16x32_bf16 v[24:27], v[136:139], v[198:201], v[24:27]
	v_mfma_f32_16x16x32_bf16 v[12:15], v[128:131], v[214:217], v[12:15]
	v_mfma_f32_16x16x32_bf16 v[8:11], v[136:139], v[214:217], v[8:11]
	v_mfma_f32_16x16x32_bf16 v[60:63], v[132:135], v[186:189], v[60:63]
	v_mfma_f32_16x16x32_bf16 v[56:59], v[140:143], v[186:189], v[56:59]
	v_mfma_f32_16x16x32_bf16 v[44:47], v[132:135], v[194:197], v[44:47]
	v_mfma_f32_16x16x32_bf16 v[40:43], v[140:143], v[194:197], v[40:43]
	v_mfma_f32_16x16x32_bf16 v[28:31], v[132:135], v[210:213], v[28:31]
	v_mfma_f32_16x16x32_bf16 v[24:27], v[140:143], v[210:213], v[24:27]
	v_mfma_f32_16x16x32_bf16 v[12:15], v[132:135], v[218:221], v[12:15]
	v_mfma_f32_16x16x32_bf16 v[8:11], v[140:143], v[218:221], v[8:11]
	v_mfma_f32_16x16x32_bf16 v[52:55], v[162:165], v[178:181], v[52:55]
	v_mfma_f32_16x16x32_bf16 v[48:51], v[170:173], v[178:181], v[48:51]
	v_mfma_f32_16x16x32_bf16 v[36:39], v[162:165], v[190:193], v[36:39]
	v_mfma_f32_16x16x32_bf16 v[32:35], v[170:173], v[190:193], v[32:35]
	v_mfma_f32_16x16x32_bf16 v[20:23], v[162:165], v[198:201], v[20:23]
	v_mfma_f32_16x16x32_bf16 v[16:19], v[170:173], v[198:201], v[16:19]
	v_mfma_f32_16x16x32_bf16 v[4:7], v[162:165], v[214:217], v[4:7]
	v_mfma_f32_16x16x32_bf16 v[0:3], v[170:173], v[214:217], v[0:3]
	v_mfma_f32_16x16x32_bf16 v[52:55], v[166:169], v[186:189], v[52:55]
	v_mfma_f32_16x16x32_bf16 v[48:51], v[174:177], v[186:189], v[48:51]
	v_mfma_f32_16x16x32_bf16 v[36:39], v[166:169], v[194:197], v[36:39]
	v_mfma_f32_16x16x32_bf16 v[32:35], v[174:177], v[194:197], v[32:35]
	v_mfma_f32_16x16x32_bf16 v[20:23], v[166:169], v[210:213], v[20:23]
	v_mfma_f32_16x16x32_bf16 v[16:19], v[174:177], v[210:213], v[16:19]
	v_mfma_f32_16x16x32_bf16 v[4:7], v[166:169], v[218:221], v[4:7]
	v_mfma_f32_16x16x32_bf16 v[0:3], v[174:177], v[218:221], v[0:3]
	s_setprio 0
	s_barrier
; #define PG8_STAGE(bufoff, gbase, voff) do { unsigned long long _gb = (unsigned long long)(gbase); asm volatile("" : "+s"(_gb)); _Pragma("unroll") for (int _i = 0; _i < 2; ++_i) \
;         __builtin_amdgcn_global_load_lds((const GAS unsigned*)((const GAS char*)_gb + (voff)[_i]), (LAS unsigned*)(lds + (bufoff) + ldsw + _i * 8192), 16, 0, 0); } while (0)
; #define PG8_LDA(dst, b, h) do { _Pragma("unroll") for (int m = 0; m < 4; ++m) _Pragma("unroll") for (int k = 0; k < 2; ++k) dst[m][k] = *(const LAS bf16x8*)(lds + PG8_SA(b, h) + aoff + m * 2048 + k * 1024); } while (0)
; #define PG8_LDB(dst, b, h) do { _Pragma("unroll") for (int n = 0; n < 2; ++n) _Pragma("unroll") for (int k = 0; k < 2; ++k) dst[n][k] = *(const LAS bf16x8*)(lds + PG8_SB(b, h) + boff + n * 2048 + k * 1024); } while (0)
; #define PG8_MMA(ai, bj, At, Bt) do { __builtin_amdgcn_s_setprio(1); _Pragma("unroll") for (int m = 0; m < 4; ++m) _Pragma("unroll") for (int n = 0; n < 2; ++n) _Pragma("unroll") for (int k = 0; k < 2; ++k) \
;         acc[ai][bj][m][n] = __builtin_amdgcn_mfma_f32_16x16x32_bf16(Bt[n][k], At[m][k], acc[ai][bj][m][n], 0, 0, 0); __builtin_amdgcn_s_setprio(0); } while (0)
; #define PG8_WAIT_V(n) asm volatile("s_waitcnt vmcnt(" #n ")" ::: "memory")
; #define PG8_WAIT_L(n) asm volatile("s_waitcnt lgkmcnt(" #n ")" ::: "memory")
; #define PG8_BAR __builtin_amdgcn_s_barrier()
; #define PG8_SCHED __builtin_amdgcn_sched_barrier(0)
; template <class Epi, bool ALIGN_EPI>
; __device__ __forceinline__ void gemm_phase(LAS unsigned char* lds, const Gemm g, const StaticOrder& S, const Epi& E, const int wid) {
;     ...
;             PG8_LDB(B0, 1, 0); PG8_LDB(B1, 1, 1); PG8_SCHED; PG8_LDA(At, 1, 0); PG8_STAGE(PG8_SA(0, 1), a2 + hstep, voffA);
;             PG8_WAIT_V(8); PG8_WAIT_L(0); PG8_BAR; PG8_MMA(0, 0, At, B0); PG8_MMA(0, 1, At, B1); PG8_BAR; PG8_SCHED;
;             PG8_LDA(At, 1, 1); PG8_STAGE(PG8_SB(1, 0), b3, voffB); PG8_STAGE(PG8_SB(1, 1), b3 + hstepB, voffB); PG8_STAGE(PG8_SA(1, 0), a3, voffA);
;             PG8_WAIT_V(8); PG8_WAIT_L(0); PG8_BAR; PG8_MMA(1, 0, At, B0); PG8_MMA(1, 1, At, B1); PG8_BAR; PG8_SCHED;
;         }
;         if constexpr (ALIGN_EPI) { if (wr == 0) PG8_BAR; }
	s_add_i32 s75, 0, 0x18000
	s_add_i32 s76, 0, 0x1c000
	v_add_u32_e32 v140, s75, v203
	v_add_u32_e32 v152, s76, v203
	ds_read_b128 v[128:131], v140
	ds_read_b128 v[132:135], v140 offset:1024
	ds_read_b128 v[136:139], v140 offset:2048
	ds_read_b128 v[140:143], v140 offset:3072
	ds_read_b128 v[162:165], v152
	ds_read_b128 v[166:169], v152 offset:1024
	ds_read_b128 v[170:173], v152 offset:2048
	ds_read_b128 v[174:177], v152 offset:3072
	s_add_u32 s2, s52, 0x80000
	s_addc_u32 s3, s53, 0
	s_mov_b32 m0, s57
	ds_read_b128 v[178:181], v206 offset:32768
	ds_read_b128 v[186:189], v206 offset:33792
	ds_read_b128 v[190:193], v206 offset:34816
	ds_read_b128 v[194:197], v206 offset:35840
	ds_read_b128 v[198:201], v206 offset:36864
	ds_read_b128 v[210:213], v206 offset:37888
	ds_read_b128 v[214:217], v206 offset:38912
	ds_read_b128 v[218:221], v206 offset:39936
	s_nop 0
	global_load_lds_dwordx4 v144, s[2:3]
	s_mov_b32 m0, s58
	s_nop 0
	global_load_lds_dwordx4 v148, s[2:3]
	s_waitcnt vmcnt(8) lgkmcnt(0)
	s_barrier
	s_setprio 1
	v_mfma_f32_16x16x32_bf16 v[124:127], v[128:131], v[178:181], v[124:127]
	v_mfma_f32_16x16x32_bf16 v[120:123], v[136:139], v[178:181], v[120:123]
	v_mfma_f32_16x16x32_bf16 v[108:111], v[128:131], v[190:193], v[108:111]
	v_mfma_f32_16x16x32_bf16 v[104:107], v[136:139], v[190:193], v[104:107]
	v_mfma_f32_16x16x32_bf16 v[92:95], v[128:131], v[198:201], v[92:95]
	v_mfma_f32_16x16x32_bf16 v[88:91], v[136:139], v[198:201], v[88:91]
	v_mfma_f32_16x16x32_bf16 v[76:79], v[128:131], v[214:217], v[76:79]
	v_mfma_f32_16x16x32_bf16 v[72:75], v[136:139], v[214:217], v[72:75]
	v_mfma_f32_16x16x32_bf16 v[124:127], v[132:135], v[186:189], v[124:127]
	v_mfma_f32_16x16x32_bf16 v[120:123], v[140:143], v[186:189], v[120:123]
	v_mfma_f32_16x16x32_bf16 v[108:111], v[132:135], v[194:197], v[108:111]
	v_mfma_f32_16x16x32_bf16 v[104:107], v[140:143], v[194:197], v[104:107]
	v_mfma_f32_16x16x32_bf16 v[92:95], v[132:135], v[210:213], v[92:95]
	v_mfma_f32_16x16x32_bf16 v[88:91], v[140:143], v[210:213], v[88:91]
	v_mfma_f32_16x16x32_bf16 v[76:79], v[132:135], v[218:221], v[76:79]
	v_mfma_f32_16x16x32_bf16 v[72:75], v[140:143], v[218:221], v[72:75]
	v_mfma_f32_16x16x32_bf16 v[116:119], v[162:165], v[178:181], v[116:119]
	v_mfma_f32_16x16x32_bf16 v[112:115], v[170:173], v[178:181], v[112:115]
	v_mfma_f32_16x16x32_bf16 v[100:103], v[162:165], v[190:193], v[100:103]
	v_mfma_f32_16x16x32_bf16 v[96:99], v[170:173], v[190:193], v[96:99]
	v_mfma_f32_16x16x32_bf16 v[84:87], v[162:165], v[198:201], v[84:87]
	v_mfma_f32_16x16x32_bf16 v[80:83], v[170:173], v[198:201], v[80:83]
	v_mfma_f32_16x16x32_bf16 v[68:71], v[162:165], v[214:217], v[68:71]
	v_mfma_f32_16x16x32_bf16 v[64:67], v[170:173], v[214:217], v[64:67]
	v_mfma_f32_16x16x32_bf16 v[116:119], v[166:169], v[186:189], v[116:119]
	v_mfma_f32_16x16x32_bf16 v[112:115], v[174:177], v[186:189], v[112:115]
	v_mfma_f32_16x16x32_bf16 v[100:103], v[166:169], v[194:197], v[100:103]
	v_mfma_f32_16x16x32_bf16 v[96:99], v[174:177], v[194:197], v[96:99]
	v_mfma_f32_16x16x32_bf16 v[84:87], v[166:169], v[210:213], v[84:87]
	v_mfma_f32_16x16x32_bf16 v[80:83], v[174:177], v[210:213], v[80:83]
	v_mfma_f32_16x16x32_bf16 v[68:71], v[166:169], v[218:221], v[68:71]
	v_mfma_f32_16x16x32_bf16 v[64:67], v[174:177], v[218:221], v[64:67]
	s_setprio 0
	s_barrier
	s_add_u32 s2, s50, 0x80
	s_addc_u32 s3, s51, 0
	s_add_i32 s52, s75, s33
	ds_read_b128 v[178:181], v206 offset:49152
	ds_read_b128 v[186:189], v206 offset:50176
	ds_read_b128 v[190:193], v206 offset:51200
	ds_read_b128 v[194:197], v206 offset:52224
	ds_read_b128 v[198:201], v206 offset:53248
	ds_read_b128 v[210:213], v206 offset:54272
	ds_read_b128 v[214:217], v206 offset:55296
	s_mov_b32 m0, s52
	ds_read_b128 v[218:221], v206 offset:56320
	global_load_lds_dwordx4 v146, s[2:3]
	s_add_i32 m0, s52, 0x2000
	s_nop 0
	global_load_lds_dwordx4 v150, s[2:3]
	s_add_u32 s2, s50, 0x20080
	s_addc_u32 s3, s51, 0
	s_add_i32 s50, s76, s33
	s_mov_b32 m0, s50
	s_nop 0
	global_load_lds_dwordx4 v146, s[2:3]
	s_add_i32 m0, s50, 0x2000
	s_nop 0
	global_load_lds_dwordx4 v150, s[2:3]
	s_mov_b32 m0, s63
	s_nop 0
	global_load_lds_dwordx4 v144, s[48:49]
	s_mov_b32 m0, s64
	s_nop 0
	global_load_lds_dwordx4 v148, s[48:49]
	s_waitcnt vmcnt(8) lgkmcnt(0)
	s_barrier
	s_setprio 1
	v_mfma_f32_16x16x32_bf16 v[60:63], v[128:131], v[178:181], v[60:63]
	v_mfma_f32_16x16x32_bf16 v[56:59], v[136:139], v[178:181], v[56:59]
	v_mfma_f32_16x16x32_bf16 v[44:47], v[128:131], v[190:193], v[44:47]
	v_mfma_f32_16x16x32_bf16 v[40:43], v[136:139], v[190:193], v[40:43]
	v_mfma_f32_16x16x32_bf16 v[28:31], v[128:131], v[198:201], v[28:31]
	v_mfma_f32_16x16x32_bf16 v[24:27], v[136:139], v[198:201], v[24:27]
	v_mfma_f32_16x16x32_bf16 v[12:15], v[128:131], v[214:217], v[12:15]
	v_mfma_f32_16x16x32_bf16 v[8:11], v[136:139], v[214:217], v[8:11]
	v_mfma_f32_16x16x32_bf16 v[60:63], v[132:135], v[186:189], v[60:63]
	v_mfma_f32_16x16x32_bf16 v[56:59], v[140:143], v[186:189], v[56:59]
	v_mfma_f32_16x16x32_bf16 v[44:47], v[132:135], v[194:197], v[44:47]
	v_mfma_f32_16x16x32_bf16 v[40:43], v[140:143], v[194:197], v[40:43]
	v_mfma_f32_16x16x32_bf16 v[28:31], v[132:135], v[210:213], v[28:31]
	v_mfma_f32_16x16x32_bf16 v[24:27], v[140:143], v[210:213], v[24:27]
	v_mfma_f32_16x16x32_bf16 v[12:15], v[132:135], v[218:221], v[12:15]
	v_mfma_f32_16x16x32_bf16 v[8:11], v[140:143], v[218:221], v[8:11]
	v_mfma_f32_16x16x32_bf16 v[52:55], v[162:165], v[178:181], v[52:55]
	v_mfma_f32_16x16x32_bf16 v[48:51], v[170:173], v[178:181], v[48:51]
	v_mfma_f32_16x16x32_bf16 v[36:39], v[162:165], v[190:193], v[36:39]
	v_mfma_f32_16x16x32_bf16 v[32:35], v[170:173], v[190:193], v[32:35]
	v_mfma_f32_16x16x32_bf16 v[20:23], v[162:165], v[198:201], v[20:23]
	v_mfma_f32_16x16x32_bf16 v[16:19], v[170:173], v[198:201], v[16:19]
	v_mfma_f32_16x16x32_bf16 v[4:7], v[162:165], v[214:217], v[4:7]
	v_mfma_f32_16x16x32_bf16 v[0:3], v[170:173], v[214:217], v[0:3]
	v_mfma_f32_16x16x32_bf16 v[52:55], v[166:169], v[186:189], v[52:55]
	v_mfma_f32_16x16x32_bf16 v[48:51], v[174:177], v[186:189], v[48:51]
	v_mfma_f32_16x16x32_bf16 v[36:39], v[166:169], v[194:197], v[36:39]
	v_mfma_f32_16x16x32_bf16 v[32:35], v[174:177], v[194:197], v[32:35]
	v_mfma_f32_16x16x32_bf16 v[20:23], v[166:169], v[210:213], v[20:23]
	v_mfma_f32_16x16x32_bf16 v[16:19], v[174:177], v[210:213], v[16:19]
	v_mfma_f32_16x16x32_bf16 v[4:7], v[166:169], v[218:221], v[4:7]
	v_mfma_f32_16x16x32_bf16 v[0:3], v[174:177], v[218:221], v[0:3]
	s_setprio 0
	s_barrier
	s_add_i32 s74, s74, 2
	s_add_u32 s72, s72, 0x100
	s_addc_u32 s73, s73, 0
	s_cmp_gt_u32 s74, 29
	s_mov_b64 s[2:3], s[6:7]
	s_cbranch_scc0 .LBB0_105
	s_and_b64 vcc, exec, s[84:85]
	s_cbranch_vccz .LBB0_108
	s_barrier

; #define PG8_STAGE(bufoff, gbase, voff) do { unsigned long long _gb = (unsigned long long)(gbase); asm volatile("" : "+s"(_gb)); _Pragma("unroll") for (int _i = 0; _i < 2; ++_i) \
;         __builtin_amdgcn_global_load_lds((const GAS unsigned*)((const GAS char*)_gb + (voff)[_i]), (LAS unsigned*)(lds + (bufoff) + ldsw + _i * 8192), 16, 0, 0); } while (0)
; #define PG8_LDA(dst, b, h) do { _Pragma("unroll") for (int m = 0; m < 4; ++m) _Pragma("unroll") for (int k = 0; k < 2; ++k) dst[m][k] = *(const LAS bf16x8*)(lds + PG8_SA(b, h) + aoff + m * 2048 + k * 1024); } while (0)
; #define PG8_LDB(dst, b, h) do { _Pragma("unroll") for (int n = 0; n < 2; ++n) _Pragma("unroll") for (int k = 0; k < 2; ++k) dst[n][k] = *(const LAS bf16x8*)(lds + PG8_SB(b, h) + boff + n * 2048 + k * 1024); } while (0)
; #define PG8_WAIT_V(n) asm volatile("s_waitcnt vmcnt(" #n ")" ::: "memory")
; #define PG8_WAIT_L(n) asm volatile("s_waitcnt lgkmcnt(" #n ")" ::: "memory")
; #define PG8_BAR __builtin_amdgcn_s_barrier()
; #define PG8_SCHED __builtin_amdgcn_sched_barrier(0)
; template <class Epi, bool ALIGN_EPI>
; __device__ __forceinline__ void gemm_phase(LAS unsigned char* lds, const Gemm g, const StaticOrder& S, const Epi& E, const int wid) {
;     ...
;         const bool has_next = S.next(ui + 1, nxt);
;         const char* nA = has_next ? (const char*)g.A + (size_t)nxt.pm * tstep : cA; const char* nB = has_next ? (const char*)g.Bt + (size_t)nxt.pn * tstep : cB;
;         for (int t = 0; t < nt; t += 2) {
;             const bool last = (t == nt - 2);
;             const char* a1 = cA + (size_t)(t + 1) * kstep;
;             const char* a2 = last ? nA : cA + (size_t)(t + 2) * kstep; const char* b2 = last ? nB : cB + (size_t)(t + 2) * kstep;
;             const char* a3 = a2 + kstep; const char* b3 = b2 + kstep;
;             PG8_LDB(B0, 0, 0); PG8_LDB(B1, 0, 1); PG8_SCHED; PG8_LDA(At, 0, 0); PG8_STAGE(PG8_SA(1, 1), a1 + hstep, voffA);
;             PG8_WAIT_V(8); PG8_WAIT_L(0); PG8_BAR; PG8_MMA(0, 0, At, B0); PG8_MMA(0, 1, At, B1); PG8_BAR; PG8_SCHED;
;             PG8_LDA(At, 0, 1); PG8_STAGE(PG8_SB(0, 0), b2, voffB); PG8_STAGE(PG8_SB(0, 1), b2 + hstepB, voffB); PG8_STAGE(PG8_SA(0, 0), a2, voffA);
;             PG8_WAIT_V(8); PG8_WAIT_L(0); PG8_BAR; PG8_MMA(1, 0, At, B0); PG8_MMA(1, 1, At, B1); PG8_BAR; PG8_SCHED;
.LBB0_488:
	s_ashr_i32 s19, s18, 31
	s_lshl_b64 s[22:23], s[18:19], 17
	s_add_u32 s22, s42, s22
	s_addc_u32 s23, s43, s23
	s_and_b64 s[26:27], s[4:5], exec
	ds_read_b128 v[0:3], v141
	ds_read_b128 v[4:7], v141 offset:1024
	ds_read_b128 v[8:11], v141 offset:2048
	ds_read_b128 v[12:15], v141 offset:3072
	ds_read_b128 v[16:19], v142
	ds_read_b128 v[20:23], v142 offset:1024
	ds_read_b128 v[24:27], v142 offset:2048
	ds_read_b128 v[28:31], v142 offset:3072
	s_cselect_b32 s37, s23, s29
	s_cselect_b32 s36, s22, s28
	s_ashr_i32 s17, s16, 31
	s_lshl_b64 s[26:27], s[16:17], 17
	s_add_u32 s26, s24, s26
	s_addc_u32 s27, s25, s27
	s_and_b64 s[30:31], s[4:5], exec
	s_cselect_b32 s31, s27, s35
	s_cselect_b32 s30, s26, s34
	s_add_u32 s40, s28, 0x100
	s_addc_u32 s41, s29, 0
	s_add_u32 s56, s34, 0x100
	s_addc_u32 s57, s35, 0
	s_add_u32 s38, s28, 0x180
	s_addc_u32 s39, s29, 0
	s_add_u32 s58, s28, 0x10080
	s_addc_u32 s59, s29, 0
	s_add_i32 s62, s44, 0xc000
	ds_read_b128 v[32:35], v143
	ds_read_b128 v[36:39], v143 offset:1024
	ds_read_b128 v[40:43], v143 offset:2048
	ds_read_b128 v[44:47], v143 offset:3072
	ds_read_b128 v[48:51], v143 offset:4096
	ds_read_b128 v[52:55], v143 offset:5120
	ds_read_b128 v[56:59], v143 offset:6144
	ds_read_b128 v[60:63], v143 offset:7168
	s_mov_b32 m0, s62
	v_lshl_add_u64 v[64:65], s[58:59], 0, v[134:135]
	s_add_i32 s17, s44, 0xe000
	global_load_lds_dwordx4 v[64:65], off
	v_lshl_add_u64 v[64:65], s[58:59], 0, v[130:131]
	s_mov_b32 m0, s17
	s_nop 0
	global_load_lds_dwordx4 v[64:65], off
	s_waitcnt vmcnt(8) lgkmcnt(0)
	s_barrier
	s_setprio 1
	v_mfma_f32_16x16x32_bf16 v[64:67], v[0:3], v[32:35], 0
	v_mfma_f32_16x16x32_bf16 v[68:71], v[8:11], v[32:35], 0
	v_mfma_f32_16x16x32_bf16 v[72:75], v[0:3], v[40:43], 0
	v_mfma_f32_16x16x32_bf16 v[76:79], v[8:11], v[40:43], 0
	v_mfma_f32_16x16x32_bf16 v[80:83], v[0:3], v[48:51], 0
	v_mfma_f32_16x16x32_bf16 v[84:87], v[8:11], v[48:51], 0
	v_mfma_f32_16x16x32_bf16 v[88:91], v[0:3], v[56:59], 0
	v_mfma_f32_16x16x32_bf16 v[92:95], v[8:11], v[56:59], 0
	v_mfma_f32_16x16x32_bf16 v[64:67], v[4:7], v[36:39], v[64:67]
	v_mfma_f32_16x16x32_bf16 v[68:71], v[12:15], v[36:39], v[68:71]
	v_mfma_f32_16x16x32_bf16 v[72:75], v[4:7], v[44:47], v[72:75]
	v_mfma_f32_16x16x32_bf16 v[76:79], v[12:15], v[44:47], v[76:79]
	v_mfma_f32_16x16x32_bf16 v[80:83], v[4:7], v[52:55], v[80:83]
	v_mfma_f32_16x16x32_bf16 v[84:87], v[12:15], v[52:55], v[84:87]
	v_mfma_f32_16x16x32_bf16 v[88:91], v[4:7], v[60:63], v[88:91]
	v_mfma_f32_16x16x32_bf16 v[92:95], v[12:15], v[60:63], v[92:95]
	v_mfma_f32_16x16x32_bf16 v[96:99], v[16:19], v[32:35], 0
	v_mfma_f32_16x16x32_bf16 v[32:35], v[24:27], v[32:35], 0
	v_mfma_f32_16x16x32_bf16 v[96:99], v[20:23], v[36:39], v[96:99]
	v_mfma_f32_16x16x32_bf16 v[32:35], v[28:31], v[36:39], v[32:35]
	v_mfma_f32_16x16x32_bf16 v[36:39], v[16:19], v[40:43], 0
	v_mfma_f32_16x16x32_bf16 v[40:43], v[24:27], v[40:43], 0
	v_mfma_f32_16x16x32_bf16 v[36:39], v[20:23], v[44:47], v[36:39]
	v_mfma_f32_16x16x32_bf16 v[40:43], v[28:31], v[44:47], v[40:43]
	v_mfma_f32_16x16x32_bf16 v[44:47], v[16:19], v[48:51], 0
	v_mfma_f32_16x16x32_bf16 v[48:51], v[24:27], v[48:51], 0
	v_mfma_f32_16x16x32_bf16 v[44:47], v[20:23], v[52:55], v[44:47]
	v_mfma_f32_16x16x32_bf16 v[48:51], v[28:31], v[52:55], v[48:51]
	v_mfma_f32_16x16x32_bf16 v[52:55], v[16:19], v[56:59], 0
	v_mfma_f32_16x16x32_bf16 v[56:59], v[24:27], v[56:59], 0
	v_mfma_f32_16x16x32_bf16 v[52:55], v[20:23], v[60:63], v[52:55]
	v_mfma_f32_16x16x32_bf16 v[56:59], v[28:31], v[60:63], v[56:59]
	s_setprio 0
	s_barrier
	s_add_i32 s59, s52, s33
	s_add_i32 s19, s59, 0x2000
	ds_read_b128 v[60:63], v143 offset:16384
	ds_read_b128 v[100:103], v143 offset:17408
	ds_read_b128 v[104:107], v143 offset:18432
	ds_read_b128 v[108:111], v143 offset:19456
	ds_read_b128 v[112:115], v143 offset:20480
	ds_read_b128 v[116:119], v143 offset:21504
	ds_read_b128 v[120:123], v143 offset:22528
	ds_read_b128 v[124:127], v143 offset:23552
	s_mov_b32 m0, s59
	v_lshl_add_u64 v[144:145], s[56:57], 0, v[132:133]
	s_add_u32 s64, s34, 0x4100
	global_load_lds_dwordx4 v[144:145], off
	v_lshl_add_u64 v[144:145], s[56:57], 0, v[128:129]
	s_mov_b32 m0, s19
	s_addc_u32 s65, s35, 0
	s_add_i32 s56, s53, s33
	global_load_lds_dwordx4 v[144:145], off
	s_mov_b32 m0, s56
	v_lshl_add_u64 v[144:145], s[64:65], 0, v[132:133]
	s_add_i32 s57, s56, 0x2000
	global_load_lds_dwordx4 v[144:145], off
	v_lshl_add_u64 v[144:145], s[64:65], 0, v[128:129]
	s_mov_b32 m0, s57
	s_nop 0
	global_load_lds_dwordx4 v[144:145], off
	s_mov_b32 m0, s44
	v_lshl_add_u64 v[144:145], s[40:41], 0, v[134:135]
	global_load_lds_dwordx4 v[144:145], off
	v_lshl_add_u64 v[144:145], s[40:41], 0, v[130:131]
	s_mov_b32 m0, s45
	s_nop 0
	global_load_lds_dwordx4 v[144:145], off
	s_waitcnt vmcnt(8) lgkmcnt(0)
	s_barrier
; #define PG8_STAGE(bufoff, gbase, voff) do { unsigned long long _gb = (unsigned long long)(gbase); asm volatile("" : "+s"(_gb)); _Pragma("unroll") for (int _i = 0; _i < 2; ++_i) \
;         __builtin_amdgcn_global_load_lds((const GAS unsigned*)((const GAS char*)_gb + (voff)[_i]), (LAS unsigned*)(lds + (bufoff) + ldsw + _i * 8192), 16, 0, 0); } while (0)
; #define PG8_LDA(dst, b, h) do { _Pragma("unroll") for (int m = 0; m < 4; ++m) _Pragma("unroll") for (int k = 0; k < 2; ++k) dst[m][k] = *(const LAS bf16x8*)(lds + PG8_SA(b, h) + aoff + m * 2048 + k * 1024); } while (0)
; #define PG8_LDB(dst, b, h) do { _Pragma("unroll") for (int n = 0; n < 2; ++n) _Pragma("unroll") for (int k = 0; k < 2; ++k) dst[n][k] = *(const LAS bf16x8*)(lds + PG8_SB(b, h) + boff + n * 2048 + k * 1024); } while (0)
; #define PG8_MMA(ai, bj, At, Bt) do { __builtin_amdgcn_s_setprio(1); _Pragma("unroll") for (int m = 0; m < 4; ++m) _Pragma("unroll") for (int n = 0; n < 2; ++n) _Pragma("unroll") for (int k = 0; k < 2; ++k) \
;         acc[ai][bj][m][n] = __builtin_amdgcn_mfma_f32_16x16x32_bf16(Bt[n][k], At[m][k], acc[ai][bj][m][n], 0, 0, 0); __builtin_amdgcn_s_setprio(0); } while (0)
; #define PG8_WAIT_V(n) asm volatile("s_waitcnt vmcnt(" #n ")" ::: "memory")
; #define PG8_WAIT_L(n) asm volatile("s_waitcnt lgkmcnt(" #n ")" ::: "memory")
; #define PG8_BAR __builtin_amdgcn_s_barrier()
; #define PG8_SCHED __builtin_amdgcn_sched_barrier(0)
; template <class Epi, bool ALIGN_EPI>
; __device__ __forceinline__ void gemm_phase(LAS unsigned char* lds, const Gemm g, const StaticOrder& S, const Epi& E, const int wid) {
;     ...
;             PG8_WAIT_V(8); PG8_WAIT_L(0); PG8_BAR; PG8_MMA(1, 0, At, B0); PG8_MMA(1, 1, At, B1); PG8_BAR; PG8_SCHED;
;             PG8_LDB(B0, 1, 0); PG8_LDB(B1, 1, 1); PG8_SCHED; PG8_LDA(At, 1, 0); PG8_STAGE(PG8_SA(0, 1), a2 + hstep, voffA);
;             PG8_WAIT_V(8); PG8_WAIT_L(0); PG8_BAR; PG8_MMA(0, 0, At, B0); PG8_MMA(0, 1, At, B1); PG8_BAR; PG8_SCHED;
	s_setprio 1
	v_mfma_f32_16x16x32_bf16 v[144:147], v[0:3], v[60:63], 0
	v_mfma_f32_16x16x32_bf16 v[152:155], v[0:3], v[104:107], 0
	v_mfma_f32_16x16x32_bf16 v[160:163], v[0:3], v[112:115], 0
	v_mfma_f32_16x16x32_bf16 v[0:3], v[0:3], v[120:123], 0
	v_mfma_f32_16x16x32_bf16 v[144:147], v[4:7], v[100:103], v[144:147]
	v_mfma_f32_16x16x32_bf16 v[152:155], v[4:7], v[108:111], v[152:155]
	v_mfma_f32_16x16x32_bf16 v[160:163], v[4:7], v[116:119], v[160:163]
	v_mfma_f32_16x16x32_bf16 v[0:3], v[4:7], v[124:127], v[0:3]
	v_mfma_f32_16x16x32_bf16 v[4:7], v[8:11], v[120:123], 0
	v_mfma_f32_16x16x32_bf16 v[148:151], v[8:11], v[60:63], 0
	v_mfma_f32_16x16x32_bf16 v[156:159], v[8:11], v[104:107], 0
	v_mfma_f32_16x16x32_bf16 v[164:167], v[8:11], v[112:115], 0
	v_mfma_f32_16x16x32_bf16 v[4:7], v[12:15], v[124:127], v[4:7]
	v_mfma_f32_16x16x32_bf16 v[148:151], v[12:15], v[100:103], v[148:151]
	v_mfma_f32_16x16x32_bf16 v[156:159], v[12:15], v[108:111], v[156:159]
	v_mfma_f32_16x16x32_bf16 v[164:167], v[12:15], v[116:119], v[164:167]
	v_mfma_f32_16x16x32_bf16 v[8:11], v[16:19], v[60:63], 0
	v_mfma_f32_16x16x32_bf16 v[12:15], v[24:27], v[60:63], 0
	v_mfma_f32_16x16x32_bf16 v[8:11], v[20:23], v[100:103], v[8:11]
	v_mfma_f32_16x16x32_bf16 v[12:15], v[28:31], v[100:103], v[12:15]
	v_mfma_f32_16x16x32_bf16 v[60:63], v[16:19], v[104:107], 0
	v_mfma_f32_16x16x32_bf16 v[100:103], v[24:27], v[104:107], 0
	v_mfma_f32_16x16x32_bf16 v[104:107], v[16:19], v[112:115], 0
	v_mfma_f32_16x16x32_bf16 v[16:19], v[16:19], v[120:123], 0
	v_mfma_f32_16x16x32_bf16 v[60:63], v[20:23], v[108:111], v[60:63]
	v_mfma_f32_16x16x32_bf16 v[100:103], v[28:31], v[108:111], v[100:103]
	v_mfma_f32_16x16x32_bf16 v[104:107], v[20:23], v[116:119], v[104:107]
	v_mfma_f32_16x16x32_bf16 v[108:111], v[24:27], v[112:115], 0
	v_mfma_f32_16x16x32_bf16 v[16:19], v[20:23], v[124:127], v[16:19]
	v_mfma_f32_16x16x32_bf16 v[20:23], v[24:27], v[120:123], 0
	v_mfma_f32_16x16x32_bf16 v[108:111], v[28:31], v[116:119], v[108:111]
	v_mfma_f32_16x16x32_bf16 v[20:23], v[28:31], v[124:127], v[20:23]
	s_setprio 0
	s_barrier
	s_add_i32 s63, 0, 0x18000
	s_add_i32 s58, 0, 0x1c000
	v_add_u32_e32 v184, s63, v140
	v_add_u32_e32 v236, s58, v140
	ds_read_b128 v[24:27], v184
	ds_read_b128 v[28:31], v184 offset:1024
	ds_read_b128 v[112:115], v184 offset:2048
	ds_read_b128 v[116:119], v184 offset:3072
	ds_read_b128 v[120:123], v236
	ds_read_b128 v[124:127], v236 offset:1024
	ds_read_b128 v[168:171], v236 offset:2048
	ds_read_b128 v[172:175], v236 offset:3072
	s_add_u32 s40, s28, 0x10100
	s_addc_u32 s41, s29, 0
	s_mov_b32 m0, s46
	ds_read_b128 v[176:179], v143 offset:32768
	ds_read_b128 v[180:183], v143 offset:33792
	ds_read_b128 v[186:189], v143 offset:34816
	ds_read_b128 v[190:193], v143 offset:35840
	ds_read_b128 v[194:197], v143 offset:36864
	ds_read_b128 v[198:201], v143 offset:37888
	ds_read_b128 v[204:207], v143 offset:38912
	ds_read_b128 v[208:211], v143 offset:39936
	s_nop 0
	v_lshl_add_u64 v[202:203], s[40:41], 0, v[134:135]
	global_load_lds_dwordx4 v[202:203], off
	v_lshl_add_u64 v[202:203], s[40:41], 0, v[130:131]
	s_mov_b32 m0, s47
	s_nop 0
	global_load_lds_dwordx4 v[202:203], off
	s_waitcnt vmcnt(8) lgkmcnt(0)
	s_barrier
	s_setprio 1
	v_mfma_f32_16x16x32_bf16 v[64:67], v[24:27], v[176:179], v[64:67]
	v_mfma_f32_16x16x32_bf16 v[68:71], v[112:115], v[176:179], v[68:71]
	v_mfma_f32_16x16x32_bf16 v[72:75], v[24:27], v[186:189], v[72:75]
	v_mfma_f32_16x16x32_bf16 v[76:79], v[112:115], v[186:189], v[76:79]
	v_mfma_f32_16x16x32_bf16 v[80:83], v[24:27], v[194:197], v[80:83]
	v_mfma_f32_16x16x32_bf16 v[84:87], v[112:115], v[194:197], v[84:87]
	v_mfma_f32_16x16x32_bf16 v[88:91], v[24:27], v[204:207], v[88:91]
	v_mfma_f32_16x16x32_bf16 v[92:95], v[112:115], v[204:207], v[92:95]
	v_mfma_f32_16x16x32_bf16 v[64:67], v[28:31], v[180:183], v[64:67]
	v_mfma_f32_16x16x32_bf16 v[68:71], v[116:119], v[180:183], v[68:71]
	v_mfma_f32_16x16x32_bf16 v[72:75], v[28:31], v[190:193], v[72:75]
	v_mfma_f32_16x16x32_bf16 v[76:79], v[116:119], v[190:193], v[76:79]
	v_mfma_f32_16x16x32_bf16 v[80:83], v[28:31], v[198:201], v[80:83]
	v_mfma_f32_16x16x32_bf16 v[84:87], v[116:119], v[198:201], v[84:87]
	v_mfma_f32_16x16x32_bf16 v[88:91], v[28:31], v[208:211], v[88:91]
	v_mfma_f32_16x16x32_bf16 v[92:95], v[116:119], v[208:211], v[92:95]
	v_mfma_f32_16x16x32_bf16 v[96:99], v[120:123], v[176:179], v[96:99]
	v_mfma_f32_16x16x32_bf16 v[32:35], v[168:171], v[176:179], v[32:35]
	v_mfma_f32_16x16x32_bf16 v[36:39], v[120:123], v[186:189], v[36:39]
	v_mfma_f32_16x16x32_bf16 v[40:43], v[168:171], v[186:189], v[40:43]
	v_mfma_f32_16x16x32_bf16 v[44:47], v[120:123], v[194:197], v[44:47]
	v_mfma_f32_16x16x32_bf16 v[48:51], v[168:171], v[194:197], v[48:51]
	v_mfma_f32_16x16x32_bf16 v[52:55], v[120:123], v[204:207], v[52:55]
	v_mfma_f32_16x16x32_bf16 v[56:59], v[168:171], v[204:207], v[56:59]
	v_mfma_f32_16x16x32_bf16 v[96:99], v[124:127], v[180:183], v[96:99]
	v_mfma_f32_16x16x32_bf16 v[32:35], v[172:175], v[180:183], v[32:35]
	v_mfma_f32_16x16x32_bf16 v[36:39], v[124:127], v[190:193], v[36:39]
	v_mfma_f32_16x16x32_bf16 v[40:43], v[172:175], v[190:193], v[40:43]
	v_mfma_f32_16x16x32_bf16 v[44:47], v[124:127], v[198:201], v[44:47]
	v_mfma_f32_16x16x32_bf16 v[48:51], v[172:175], v[198:201], v[48:51]
	v_mfma_f32_16x16x32_bf16 v[52:55], v[124:127], v[208:211], v[52:55]
	v_mfma_f32_16x16x32_bf16 v[56:59], v[172:175], v[208:211], v[56:59]
	s_setprio 0
	s_barrier
; #define PG8_STAGE(bufoff, gbase, voff) do { unsigned long long _gb = (unsigned long long)(gbase); asm volatile("" : "+s"(_gb)); _Pragma("unroll") for (int _i = 0; _i < 2; ++_i) \
;         __builtin_amdgcn_global_load_lds((const GAS unsigned*)((const GAS char*)_gb + (voff)[_i]), (LAS unsigned*)(lds + (bufoff) + ldsw + _i * 8192), 16, 0, 0); } while (0)
; #define PG8_LDA(dst, b, h) do { _Pragma("unroll") for (int m = 0; m < 4; ++m) _Pragma("unroll") for (int k = 0; k < 2; ++k) dst[m][k] = *(const LAS bf16x8*)(lds + PG8_SA(b, h) + aoff + m * 2048 + k * 1024); } while (0)
; #define PG8_LDB(dst, b, h) do { _Pragma("unroll") for (int n = 0; n < 2; ++n) _Pragma("unroll") for (int k = 0; k < 2; ++k) dst[n][k] = *(const LAS bf16x8*)(lds + PG8_SB(b, h) + boff + n * 2048 + k * 1024); } while (0)
; #define PG8_MMA(ai, bj, At, Bt) do { __builtin_amdgcn_s_setprio(1); _Pragma("unroll") for (int m = 0; m < 4; ++m) _Pragma("unroll") for (int n = 0; n < 2; ++n) _Pragma("unroll") for (int k = 0; k < 2; ++k) \
;         acc[ai][bj][m][n] = __builtin_amdgcn_mfma_f32_16x16x32_bf16(Bt[n][k], At[m][k], acc[ai][bj][m][n], 0, 0, 0); __builtin_amdgcn_s_setprio(0); } while (0)
; template <class Epi, bool ALIGN_EPI>
; __device__ __forceinline__ void gemm_phase(LAS unsigned char* lds, const Gemm g, const StaticOrder& S, const Epi& E, const int wid) {
;     ...
;             PG8_LDB(B0, 0, 0); PG8_LDB(B1, 0, 1); PG8_SCHED; PG8_LDA(At, 0, 0); PG8_STAGE(PG8_SA(1, 1), a1 + hstep, voffA);
;             PG8_WAIT_V(8); PG8_WAIT_L(0); PG8_BAR; PG8_MMA(0, 0, At, B0); PG8_MMA(0, 1, At, B1); PG8_BAR; PG8_SCHED;
;             PG8_LDA(At, 0, 1); PG8_STAGE(PG8_SB(0, 0), b2, voffB); PG8_STAGE(PG8_SB(0, 1), b2 + hstepB, voffB); PG8_STAGE(PG8_SA(0, 0), a2, voffA);
;             PG8_WAIT_V(8); PG8_WAIT_L(0); PG8_BAR; PG8_MMA(1, 0, At, B0); PG8_MMA(1, 1, At, B1); PG8_BAR; PG8_SCHED;
;             PG8_LDB(B0, 1, 0); PG8_LDB(B1, 1, 1); PG8_SCHED; PG8_LDA(At, 1, 0); PG8_STAGE(PG8_SA(0, 1), a2 + hstep, voffA);
;             PG8_WAIT_V(8); PG8_WAIT_L(0); PG8_BAR; PG8_MMA(0, 0, At, B0); PG8_MMA(0, 1, At, B1); PG8_BAR; PG8_SCHED;
;             PG8_LDA(At, 1, 1); PG8_STAGE(PG8_SB(1, 0), b3, voffB); PG8_STAGE(PG8_SB(1, 1), b3 + hstepB, voffB); PG8_STAGE(PG8_SA(1, 0), a3, voffA);
;             PG8_WAIT_V(8); PG8_WAIT_L(0); PG8_BAR; PG8_MMA(1, 0, At, B0); PG8_MMA(1, 1, At, B1); PG8_BAR; PG8_SCHED;
	s_add_u32 s40, s34, 0x180
	s_addc_u32 s41, s35, 0
	s_add_i32 s63, s63, s33
	ds_read_b128 v[176:179], v143 offset:49152
	ds_read_b128 v[180:183], v143 offset:50176
	ds_read_b128 v[186:189], v143 offset:51200
	ds_read_b128 v[190:193], v143 offset:52224
	ds_read_b128 v[194:197], v143 offset:53248
	ds_read_b128 v[198:201], v143 offset:54272
	ds_read_b128 v[204:207], v143 offset:55296
	ds_read_b128 v[208:211], v143 offset:56320
	s_mov_b32 m0, s63
	v_lshl_add_u64 v[202:203], s[40:41], 0, v[132:133]
	global_load_lds_dwordx4 v[202:203], off
	v_lshl_add_u64 v[202:203], s[40:41], 0, v[128:129]
	s_add_i32 s40, s63, 0x2000
	s_add_u32 s34, s34, 0x4180
	s_mov_b32 m0, s40
	s_addc_u32 s35, s35, 0
	s_add_i32 s41, s58, s33
	global_load_lds_dwordx4 v[202:203], off
	s_mov_b32 m0, s41
	v_lshl_add_u64 v[202:203], s[34:35], 0, v[132:133]
	s_add_i32 s58, s41, 0x2000
	global_load_lds_dwordx4 v[202:203], off
	v_lshl_add_u64 v[202:203], s[34:35], 0, v[128:129]
	s_mov_b32 m0, s58
	s_nop 0
	global_load_lds_dwordx4 v[202:203], off
	s_mov_b32 m0, s50
	v_lshl_add_u64 v[202:203], s[38:39], 0, v[134:135]
	global_load_lds_dwordx4 v[202:203], off
	v_lshl_add_u64 v[202:203], s[38:39], 0, v[130:131]
	s_mov_b32 m0, s51
	s_nop 0
	global_load_lds_dwordx4 v[202:203], off
	s_waitcnt vmcnt(8) lgkmcnt(0)
	s_barrier
	s_setprio 1
	v_mfma_f32_16x16x32_bf16 v[0:3], v[24:27], v[204:207], v[0:3]
	v_mfma_f32_16x16x32_bf16 v[4:7], v[112:115], v[204:207], v[4:7]
	v_mfma_f32_16x16x32_bf16 v[144:147], v[24:27], v[176:179], v[144:147]
	v_mfma_f32_16x16x32_bf16 v[148:151], v[112:115], v[176:179], v[148:151]
	v_mfma_f32_16x16x32_bf16 v[152:155], v[24:27], v[186:189], v[152:155]
	v_mfma_f32_16x16x32_bf16 v[156:159], v[112:115], v[186:189], v[156:159]
	v_mfma_f32_16x16x32_bf16 v[160:163], v[24:27], v[194:197], v[160:163]
	v_mfma_f32_16x16x32_bf16 v[164:167], v[112:115], v[194:197], v[164:167]
	v_mfma_f32_16x16x32_bf16 v[0:3], v[28:31], v[208:211], v[0:3]
	v_mfma_f32_16x16x32_bf16 v[4:7], v[116:119], v[208:211], v[4:7]
	v_mfma_f32_16x16x32_bf16 v[144:147], v[28:31], v[180:183], v[144:147]
	v_mfma_f32_16x16x32_bf16 v[148:151], v[116:119], v[180:183], v[148:151]
	v_mfma_f32_16x16x32_bf16 v[152:155], v[28:31], v[190:193], v[152:155]
	v_mfma_f32_16x16x32_bf16 v[156:159], v[116:119], v[190:193], v[156:159]
	v_mfma_f32_16x16x32_bf16 v[160:163], v[28:31], v[198:201], v[160:163]
	v_mfma_f32_16x16x32_bf16 v[164:167], v[116:119], v[198:201], v[164:167]
	v_mfma_f32_16x16x32_bf16 v[8:11], v[120:123], v[176:179], v[8:11]
	v_mfma_f32_16x16x32_bf16 v[12:15], v[168:171], v[176:179], v[12:15]
	v_mfma_f32_16x16x32_bf16 v[24:27], v[120:123], v[186:189], v[60:63]
	v_mfma_f32_16x16x32_bf16 v[28:31], v[168:171], v[186:189], v[100:103]
	v_mfma_f32_16x16x32_bf16 v[60:63], v[120:123], v[194:197], v[104:107]
	v_mfma_f32_16x16x32_bf16 v[100:103], v[168:171], v[194:197], v[108:111]
	v_mfma_f32_16x16x32_bf16 v[16:19], v[120:123], v[204:207], v[16:19]
	v_mfma_f32_16x16x32_bf16 v[20:23], v[168:171], v[204:207], v[20:23]
	v_mfma_f32_16x16x32_bf16 v[8:11], v[124:127], v[180:183], v[8:11]
	v_mfma_f32_16x16x32_bf16 v[12:15], v[172:175], v[180:183], v[12:15]
	v_mfma_f32_16x16x32_bf16 v[24:27], v[124:127], v[190:193], v[24:27]
	v_mfma_f32_16x16x32_bf16 v[28:31], v[172:175], v[190:193], v[28:31]
	v_mfma_f32_16x16x32_bf16 v[60:63], v[124:127], v[198:201], v[60:63]
	v_mfma_f32_16x16x32_bf16 v[100:103], v[172:175], v[198:201], v[100:103]
	v_mfma_f32_16x16x32_bf16 v[16:19], v[124:127], v[208:211], v[16:19]
	v_mfma_f32_16x16x32_bf16 v[20:23], v[172:175], v[208:211], v[20:23]
	s_setprio 0
	s_barrier
	ds_read_b128 v[104:107], v141
	ds_read_b128 v[108:111], v141 offset:1024
	ds_read_b128 v[112:115], v141 offset:2048
	ds_read_b128 v[116:119], v141 offset:3072
	ds_read_b128 v[120:123], v142
	ds_read_b128 v[124:127], v142 offset:1024
	ds_read_b128 v[168:171], v142 offset:2048
	ds_read_b128 v[172:175], v142 offset:3072
	s_add_u32 s34, s36, 0x80
	s_addc_u32 s35, s37, 0
	s_add_u32 s28, s28, 0x10180
	s_addc_u32 s29, s29, 0
	s_mov_b32 m0, s62
	ds_read_b128 v[176:179], v143
	ds_read_b128 v[180:183], v143 offset:1024
	ds_read_b128 v[186:189], v143 offset:2048
	ds_read_b128 v[190:193], v143 offset:3072
	ds_read_b128 v[194:197], v143 offset:4096
	ds_read_b128 v[198:201], v143 offset:5120
	ds_read_b128 v[204:207], v143 offset:6144
	ds_read_b128 v[208:211], v143 offset:7168
	s_nop 0
	v_lshl_add_u64 v[202:203], s[28:29], 0, v[134:135]
	global_load_lds_dwordx4 v[202:203], off
	v_lshl_add_u64 v[202:203], s[28:29], 0, v[130:131]
	s_mov_b32 m0, s17
	s_nop 0
	global_load_lds_dwordx4 v[202:203], off
	s_waitcnt vmcnt(8) lgkmcnt(0)
	s_barrier
; #define PG8_STAGE(bufoff, gbase, voff) do { unsigned long long _gb = (unsigned long long)(gbase); asm volatile("" : "+s"(_gb)); _Pragma("unroll") for (int _i = 0; _i < 2; ++_i) \
;         __builtin_amdgcn_global_load_lds((const GAS unsigned*)((const GAS char*)_gb + (voff)[_i]), (LAS unsigned*)(lds + (bufoff) + ldsw + _i * 8192), 16, 0, 0); } while (0)
; #define PG8_LDA(dst, b, h) do { _Pragma("unroll") for (int m = 0; m < 4; ++m) _Pragma("unroll") for (int k = 0; k < 2; ++k) dst[m][k] = *(const LAS bf16x8*)(lds + PG8_SA(b, h) + aoff + m * 2048 + k * 1024); } while (0)
; #define PG8_MMA(ai, bj, At, Bt) do { __builtin_amdgcn_s_setprio(1); _Pragma("unroll") for (int m = 0; m < 4; ++m) _Pragma("unroll") for (int n = 0; n < 2; ++n) _Pragma("unroll") for (int k = 0; k < 2; ++k) \
;         acc[ai][bj][m][n] = __builtin_amdgcn_mfma_f32_16x16x32_bf16(Bt[n][k], At[m][k], acc[ai][bj][m][n], 0, 0, 0); __builtin_amdgcn_s_setprio(0); } while (0)
; #define PG8_WAIT_V(n) asm volatile("s_waitcnt vmcnt(" #n ")" ::: "memory")
; #define PG8_WAIT_L(n) asm volatile("s_waitcnt lgkmcnt(" #n ")" ::: "memory")
; #define PG8_BAR __builtin_amdgcn_s_barrier()
; #define PG8_SCHED __builtin_amdgcn_sched_barrier(0)
; template <class Epi, bool ALIGN_EPI>
; __device__ __forceinline__ void gemm_phase(LAS unsigned char* lds, const Gemm g, const StaticOrder& S, const Epi& E, const int wid) {
;     ...
;             PG8_WAIT_V(8); PG8_WAIT_L(0); PG8_BAR; PG8_MMA(0, 0, At, B0); PG8_MMA(0, 1, At, B1); PG8_BAR; PG8_SCHED;
;             PG8_LDA(At, 0, 1); PG8_STAGE(PG8_SB(0, 0), b2, voffB); PG8_STAGE(PG8_SB(0, 1), b2 + hstepB, voffB); PG8_STAGE(PG8_SA(0, 0), a2, voffA);
;             PG8_WAIT_V(8); PG8_WAIT_L(0); PG8_BAR; PG8_MMA(1, 0, At, B0); PG8_MMA(1, 1, At, B1); PG8_BAR; PG8_SCHED;
	s_setprio 1
	v_mfma_f32_16x16x32_bf16 v[80:83], v[104:107], v[194:197], v[80:83]
	v_mfma_f32_16x16x32_bf16 v[212:215], v[108:111], v[198:201], v[80:83]
	v_mfma_f32_16x16x32_bf16 v[80:83], v[112:115], v[194:197], v[84:87]
	v_mfma_f32_16x16x32_bf16 v[216:219], v[116:119], v[198:201], v[80:83]
	v_mfma_f32_16x16x32_bf16 v[80:83], v[104:107], v[204:207], v[88:91]
	v_mfma_f32_16x16x32_bf16 v[64:67], v[104:107], v[176:179], v[64:67]
	v_mfma_f32_16x16x32_bf16 v[68:71], v[112:115], v[176:179], v[68:71]
	v_mfma_f32_16x16x32_bf16 v[72:75], v[104:107], v[186:189], v[72:75]
	v_mfma_f32_16x16x32_bf16 v[76:79], v[112:115], v[186:189], v[76:79]
	v_mfma_f32_16x16x32_bf16 v[88:91], v[108:111], v[208:211], v[80:83]
	v_mfma_f32_16x16x32_bf16 v[80:83], v[112:115], v[204:207], v[92:95]
	v_mfma_f32_16x16x32_bf16 v[64:67], v[108:111], v[180:183], v[64:67]
	v_mfma_f32_16x16x32_bf16 v[68:71], v[116:119], v[180:183], v[68:71]
	v_mfma_f32_16x16x32_bf16 v[72:75], v[108:111], v[190:193], v[72:75]
	v_mfma_f32_16x16x32_bf16 v[76:79], v[116:119], v[190:193], v[76:79]
	v_mfma_f32_16x16x32_bf16 v[92:95], v[116:119], v[208:211], v[80:83]
	v_mfma_f32_16x16x32_bf16 v[48:51], v[168:171], v[194:197], v[48:51]
	v_mfma_f32_16x16x32_bf16 v[80:83], v[120:123], v[176:179], v[96:99]
	v_mfma_f32_16x16x32_bf16 v[32:35], v[168:171], v[176:179], v[32:35]
	v_mfma_f32_16x16x32_bf16 v[36:39], v[120:123], v[186:189], v[36:39]
	v_mfma_f32_16x16x32_bf16 v[40:43], v[168:171], v[186:189], v[40:43]
	v_mfma_f32_16x16x32_bf16 v[44:47], v[120:123], v[194:197], v[44:47]
	v_mfma_f32_16x16x32_bf16 v[176:179], v[172:175], v[198:201], v[48:51]
	v_mfma_f32_16x16x32_bf16 v[48:51], v[120:123], v[204:207], v[52:55]
	v_mfma_f32_16x16x32_bf16 v[96:99], v[124:127], v[180:183], v[80:83]
	v_mfma_f32_16x16x32_bf16 v[32:35], v[172:175], v[180:183], v[32:35]
	v_mfma_f32_16x16x32_bf16 v[36:39], v[124:127], v[190:193], v[36:39]
	v_mfma_f32_16x16x32_bf16 v[40:43], v[172:175], v[190:193], v[40:43]
	v_mfma_f32_16x16x32_bf16 v[44:47], v[124:127], v[198:201], v[44:47]
	v_mfma_f32_16x16x32_bf16 v[180:183], v[124:127], v[208:211], v[48:51]
	v_mfma_f32_16x16x32_bf16 v[48:51], v[168:171], v[204:207], v[56:59]
	v_mfma_f32_16x16x32_bf16 v[186:189], v[172:175], v[208:211], v[48:51]
	s_setprio 0
	s_barrier
	s_mov_b64 s[28:29], s[30:31]
	s_mov_b32 m0, s59
	s_nop 2
	ds_read_b128 v[48:51], v143 offset:16384
	ds_read_b128 v[52:55], v143 offset:17408
	ds_read_b128 v[56:59], v143 offset:18432
	ds_read_b128 v[80:83], v143 offset:19456
	ds_read_b128 v[84:87], v143 offset:20480
	ds_read_b128 v[190:193], v143 offset:21504
	ds_read_b128 v[194:197], v143 offset:22528
	ds_read_b128 v[198:201], v143 offset:23552
	s_nop 0
	v_lshl_add_u64 v[202:203], s[28:29], 0, v[132:133]
	global_load_lds_dwordx4 v[202:203], off
	v_lshl_add_u64 v[202:203], s[28:29], 0, v[128:129]
	s_add_u32 s28, s30, 0x4000
	s_mov_b32 m0, s19
	s_addc_u32 s29, s31, 0
	global_load_lds_dwordx4 v[202:203], off
	s_mov_b32 m0, s56
	v_lshl_add_u64 v[202:203], s[28:29], 0, v[132:133]
	global_load_lds_dwordx4 v[202:203], off
	v_lshl_add_u64 v[202:203], s[28:29], 0, v[128:129]
	s_mov_b32 m0, s57
	s_mov_b64 s[28:29], s[36:37]
	global_load_lds_dwordx4 v[202:203], off
	s_mov_b32 m0, s44
	v_lshl_add_u64 v[202:203], s[28:29], 0, v[134:135]
	global_load_lds_dwordx4 v[202:203], off
	v_lshl_add_u64 v[202:203], s[28:29], 0, v[130:131]
	s_mov_b32 m0, s45
	s_nop 0
	global_load_lds_dwordx4 v[202:203], off
	s_waitcnt vmcnt(8) lgkmcnt(0)
	s_barrier
	s_setprio 1
	v_mfma_f32_16x16x32_bf16 v[0:3], v[104:107], v[194:197], v[0:3]
	v_mfma_f32_16x16x32_bf16 v[4:7], v[112:115], v[194:197], v[4:7]
	v_mfma_f32_16x16x32_bf16 v[144:147], v[104:107], v[48:51], v[144:147]
	v_mfma_f32_16x16x32_bf16 v[148:151], v[112:115], v[48:51], v[148:151]
	v_mfma_f32_16x16x32_bf16 v[152:155], v[104:107], v[56:59], v[152:155]
	v_mfma_f32_16x16x32_bf16 v[156:159], v[112:115], v[56:59], v[156:159]
	v_mfma_f32_16x16x32_bf16 v[160:163], v[104:107], v[84:87], v[160:163]
	v_mfma_f32_16x16x32_bf16 v[164:167], v[112:115], v[84:87], v[164:167]
	v_mfma_f32_16x16x32_bf16 v[0:3], v[108:111], v[198:201], v[0:3]
	v_mfma_f32_16x16x32_bf16 v[4:7], v[116:119], v[198:201], v[4:7]
	v_mfma_f32_16x16x32_bf16 v[144:147], v[108:111], v[52:55], v[144:147]
	v_mfma_f32_16x16x32_bf16 v[148:151], v[116:119], v[52:55], v[148:151]
	v_mfma_f32_16x16x32_bf16 v[152:155], v[108:111], v[80:83], v[152:155]
	v_mfma_f32_16x16x32_bf16 v[156:159], v[116:119], v[80:83], v[156:159]
	v_mfma_f32_16x16x32_bf16 v[160:163], v[108:111], v[190:193], v[160:163]
	v_mfma_f32_16x16x32_bf16 v[164:167], v[116:119], v[190:193], v[164:167]
	v_mfma_f32_16x16x32_bf16 v[24:27], v[120:123], v[56:59], v[24:27]
	v_mfma_f32_16x16x32_bf16 v[204:207], v[124:127], v[80:83], v[24:27]
	v_mfma_f32_16x16x32_bf16 v[24:27], v[168:171], v[56:59], v[28:31]
	v_mfma_f32_16x16x32_bf16 v[8:11], v[120:123], v[48:51], v[8:11]
	v_mfma_f32_16x16x32_bf16 v[12:15], v[168:171], v[48:51], v[12:15]
	v_mfma_f32_16x16x32_bf16 v[208:211], v[172:175], v[80:83], v[24:27]
	v_mfma_f32_16x16x32_bf16 v[24:27], v[120:123], v[84:87], v[60:63]
	v_mfma_f32_16x16x32_bf16 v[16:19], v[120:123], v[194:197], v[16:19]
	v_mfma_f32_16x16x32_bf16 v[8:11], v[124:127], v[52:55], v[8:11]
	v_mfma_f32_16x16x32_bf16 v[12:15], v[172:175], v[52:55], v[12:15]
	v_mfma_f32_16x16x32_bf16 v[220:223], v[124:127], v[190:193], v[24:27]
	v_mfma_f32_16x16x32_bf16 v[24:27], v[168:171], v[84:87], v[100:103]
	v_mfma_f32_16x16x32_bf16 v[224:227], v[124:127], v[198:201], v[16:19]
	v_mfma_f32_16x16x32_bf16 v[16:19], v[168:171], v[194:197], v[20:23]
	v_mfma_f32_16x16x32_bf16 v[190:193], v[172:175], v[190:193], v[24:27]
	v_mfma_f32_16x16x32_bf16 v[168:171], v[172:175], v[198:201], v[16:19]
	s_setprio 0
	s_barrier
; #define PG8_STAGE(bufoff, gbase, voff) do { unsigned long long _gb = (unsigned long long)(gbase); asm volatile("" : "+s"(_gb)); _Pragma("unroll") for (int _i = 0; _i < 2; ++_i) \
;         __builtin_amdgcn_global_load_lds((const GAS unsigned*)((const GAS char*)_gb + (voff)[_i]), (LAS unsigned*)(lds + (bufoff) + ldsw + _i * 8192), 16, 0, 0); } while (0)
; #define PG8_LDA(dst, b, h) do { _Pragma("unroll") for (int m = 0; m < 4; ++m) _Pragma("unroll") for (int k = 0; k < 2; ++k) dst[m][k] = *(const LAS bf16x8*)(lds + PG8_SA(b, h) + aoff + m * 2048 + k * 1024); } while (0)
; #define PG8_LDB(dst, b, h) do { _Pragma("unroll") for (int n = 0; n < 2; ++n) _Pragma("unroll") for (int k = 0; k < 2; ++k) dst[n][k] = *(const LAS bf16x8*)(lds + PG8_SB(b, h) + boff + n * 2048 + k * 1024); } while (0)
; #define PG8_MMA(ai, bj, At, Bt) do { __builtin_amdgcn_s_setprio(1); _Pragma("unroll") for (int m = 0; m < 4; ++m) _Pragma("unroll") for (int n = 0; n < 2; ++n) _Pragma("unroll") for (int k = 0; k < 2; ++k) \
;         acc[ai][bj][m][n] = __builtin_amdgcn_mfma_f32_16x16x32_bf16(Bt[n][k], At[m][k], acc[ai][bj][m][n], 0, 0, 0); __builtin_amdgcn_s_setprio(0); } while (0)
; #define PG8_WAIT_V(n) asm volatile("s_waitcnt vmcnt(" #n ")" ::: "memory")
; #define PG8_WAIT_L(n) asm volatile("s_waitcnt lgkmcnt(" #n ")" ::: "memory")
; #define PG8_BAR __builtin_amdgcn_s_barrier()
; #define PG8_SCHED __builtin_amdgcn_sched_barrier(0)
; template <class Epi, bool ALIGN_EPI>
; __device__ __forceinline__ void gemm_phase(LAS unsigned char* lds, const Gemm g, const StaticOrder& S, const Epi& E, const int wid) {
;     ...
;             PG8_LDB(B0, 1, 0); PG8_LDB(B1, 1, 1); PG8_SCHED; PG8_LDA(At, 1, 0); PG8_STAGE(PG8_SA(0, 1), a2 + hstep, voffA);
;             PG8_WAIT_V(8); PG8_WAIT_L(0); PG8_BAR; PG8_MMA(0, 0, At, B0); PG8_MMA(0, 1, At, B1); PG8_BAR; PG8_SCHED;
;             PG8_LDA(At, 1, 1); PG8_STAGE(PG8_SB(1, 0), b3, voffB); PG8_STAGE(PG8_SB(1, 1), b3 + hstepB, voffB); PG8_STAGE(PG8_SA(1, 0), a3, voffA);
;             PG8_WAIT_V(8); PG8_WAIT_L(0); PG8_BAR; PG8_MMA(1, 0, At, B0); PG8_MMA(1, 1, At, B1); PG8_BAR; PG8_SCHED;
;         }
;         if constexpr (ALIGN_EPI) { if (wr == 0) PG8_BAR; }
	ds_read_b128 v[104:107], v184
	ds_read_b128 v[108:111], v184 offset:1024
	ds_read_b128 v[172:175], v184 offset:2048
	ds_read_b128 v[194:197], v184 offset:3072
	ds_read_b128 v[198:201], v236
	ds_read_b128 v[228:231], v236 offset:1024
	ds_read_b128 v[232:235], v236 offset:2048
	ds_read_b128 v[236:239], v236 offset:3072
	s_add_u32 s28, s36, 0x10000
	s_addc_u32 s29, s37, 0
	s_mov_b32 m0, s46
	ds_read_b128 v[24:27], v143 offset:32768
	ds_read_b128 v[28:31], v143 offset:33792
	ds_read_b128 v[56:59], v143 offset:34816
	ds_read_b128 v[60:63], v143 offset:35840
	ds_read_b128 v[100:103], v143 offset:36864
	ds_read_b128 v[240:243], v143 offset:37888
	ds_read_b128 v[244:247], v143 offset:38912
	ds_read_b128 v[248:251], v143 offset:39936
	s_nop 0
	v_lshl_add_u64 v[16:17], s[28:29], 0, v[134:135]
	global_load_lds_dwordx4 v[16:17], off
	v_lshl_add_u64 v[16:17], s[28:29], 0, v[130:131]
	s_mov_b32 m0, s47
	s_nop 0
	global_load_lds_dwordx4 v[16:17], off
	s_waitcnt vmcnt(8) lgkmcnt(0)
	s_barrier
	s_setprio 1
	v_mfma_f32_16x16x32_bf16 v[16:19], v[104:107], v[24:27], v[64:67]
	v_mfma_f32_16x16x32_bf16 v[112:115], v[108:111], v[28:31], v[16:19]
	v_mfma_f32_16x16x32_bf16 v[16:19], v[172:175], v[24:27], v[68:71]
	v_mfma_f32_16x16x32_bf16 v[116:119], v[194:197], v[28:31], v[16:19]
	v_mfma_f32_16x16x32_bf16 v[16:19], v[104:107], v[56:59], v[72:75]
	v_mfma_f32_16x16x32_bf16 v[80:83], v[108:111], v[60:63], v[16:19]
	v_mfma_f32_16x16x32_bf16 v[16:19], v[172:175], v[56:59], v[76:79]
	v_mfma_f32_16x16x32_bf16 v[84:87], v[194:197], v[60:63], v[16:19]
	v_mfma_f32_16x16x32_bf16 v[16:19], v[104:107], v[100:103], v[212:215]
	v_mfma_f32_16x16x32_bf16 v[48:51], v[108:111], v[240:243], v[16:19]
	v_mfma_f32_16x16x32_bf16 v[16:19], v[172:175], v[100:103], v[216:219]
	v_mfma_f32_16x16x32_bf16 v[52:55], v[194:197], v[240:243], v[16:19]
	v_mfma_f32_16x16x32_bf16 v[16:19], v[104:107], v[244:247], v[88:91]
	v_mfma_f32_16x16x32_bf16 v[20:23], v[172:175], v[244:247], v[92:95]
	v_mfma_f32_16x16x32_bf16 v[16:19], v[108:111], v[248:251], v[16:19]
	v_mfma_f32_16x16x32_bf16 v[20:23], v[194:197], v[248:251], v[20:23]
	v_mfma_f32_16x16x32_bf16 v[64:67], v[198:201], v[24:27], v[96:99]
	v_mfma_f32_16x16x32_bf16 v[24:27], v[232:235], v[24:27], v[32:35]
	v_mfma_f32_16x16x32_bf16 v[124:127], v[236:239], v[28:31], v[24:27]
	v_mfma_f32_16x16x32_bf16 v[24:27], v[198:201], v[56:59], v[36:39]
	v_mfma_f32_16x16x32_bf16 v[88:91], v[228:231], v[60:63], v[24:27]
	v_mfma_f32_16x16x32_bf16 v[24:27], v[232:235], v[56:59], v[40:43]
	v_mfma_f32_16x16x32_bf16 v[92:95], v[236:239], v[60:63], v[24:27]
	v_mfma_f32_16x16x32_bf16 v[24:27], v[198:201], v[100:103], v[44:47]
	v_mfma_f32_16x16x32_bf16 v[56:59], v[228:231], v[240:243], v[24:27]
	v_mfma_f32_16x16x32_bf16 v[24:27], v[232:235], v[100:103], v[176:179]
	v_mfma_f32_16x16x32_bf16 v[120:123], v[228:231], v[28:31], v[64:67]
	v_mfma_f32_16x16x32_bf16 v[60:63], v[236:239], v[240:243], v[24:27]
	v_mfma_f32_16x16x32_bf16 v[24:27], v[198:201], v[244:247], v[180:183]
	v_mfma_f32_16x16x32_bf16 v[28:31], v[232:235], v[244:247], v[186:189]
	v_mfma_f32_16x16x32_bf16 v[24:27], v[228:231], v[248:251], v[24:27]
	v_mfma_f32_16x16x32_bf16 v[28:31], v[236:239], v[248:251], v[28:31]
	s_setprio 0
	s_barrier
	s_add_u32 s28, s30, 0x80
	s_addc_u32 s29, s31, 0
	s_mov_b32 m0, s63
	ds_read_b128 v[40:43], v143 offset:49152
	ds_read_b128 v[44:47], v143 offset:50176
	ds_read_b128 v[76:79], v143 offset:51200
	ds_read_b128 v[176:179], v143 offset:52224
	ds_read_b128 v[180:183], v143 offset:53248
	ds_read_b128 v[186:189], v143 offset:54272
	ds_read_b128 v[212:215], v143 offset:55296
	ds_read_b128 v[216:219], v143 offset:56320
	s_nop 0
	v_lshl_add_u64 v[32:33], s[28:29], 0, v[132:133]
	global_load_lds_dwordx4 v[32:33], off
	v_lshl_add_u64 v[32:33], s[28:29], 0, v[128:129]
	s_add_u32 s28, s30, 0x4080
	s_mov_b32 m0, s40
	s_addc_u32 s29, s31, 0
	global_load_lds_dwordx4 v[32:33], off
	s_mov_b32 m0, s41
	v_lshl_add_u64 v[32:33], s[28:29], 0, v[132:133]
	global_load_lds_dwordx4 v[32:33], off
	v_lshl_add_u64 v[32:33], s[28:29], 0, v[128:129]
	s_mov_b32 m0, s58
	s_nop 0
	global_load_lds_dwordx4 v[32:33], off
	s_mov_b32 m0, s50
	v_lshl_add_u64 v[32:33], s[34:35], 0, v[134:135]
	global_load_lds_dwordx4 v[32:33], off
	v_lshl_add_u64 v[32:33], s[34:35], 0, v[130:131]
	s_mov_b32 m0, s51
	s_nop 0
	global_load_lds_dwordx4 v[32:33], off
	s_waitcnt vmcnt(8) lgkmcnt(0)
	s_barrier
	s_setprio 1
	v_mfma_f32_16x16x32_bf16 v[32:35], v[104:107], v[40:43], v[144:147]
	v_mfma_f32_16x16x32_bf16 v[96:99], v[108:111], v[44:47], v[32:35]
	v_mfma_f32_16x16x32_bf16 v[32:35], v[172:175], v[40:43], v[148:151]
	v_mfma_f32_16x16x32_bf16 v[100:103], v[194:197], v[44:47], v[32:35]
	v_mfma_f32_16x16x32_bf16 v[32:35], v[104:107], v[76:79], v[152:155]
	v_mfma_f32_16x16x32_bf16 v[64:67], v[108:111], v[176:179], v[32:35]
	v_mfma_f32_16x16x32_bf16 v[32:35], v[172:175], v[76:79], v[156:159]
	v_mfma_f32_16x16x32_bf16 v[68:71], v[194:197], v[176:179], v[32:35]
	v_mfma_f32_16x16x32_bf16 v[32:35], v[104:107], v[180:183], v[160:163]
	v_mfma_f32_16x16x32_bf16 v[36:39], v[172:175], v[180:183], v[164:167]
	v_mfma_f32_16x16x32_bf16 v[0:3], v[104:107], v[212:215], v[0:3]
	v_mfma_f32_16x16x32_bf16 v[4:7], v[172:175], v[212:215], v[4:7]
	v_mfma_f32_16x16x32_bf16 v[32:35], v[108:111], v[186:189], v[32:35]
	v_mfma_f32_16x16x32_bf16 v[36:39], v[194:197], v[186:189], v[36:39]
	v_mfma_f32_16x16x32_bf16 v[0:3], v[108:111], v[216:219], v[0:3]
	v_mfma_f32_16x16x32_bf16 v[4:7], v[194:197], v[216:219], v[4:7]
	v_mfma_f32_16x16x32_bf16 v[8:11], v[198:201], v[40:43], v[8:11]
	v_mfma_f32_16x16x32_bf16 v[104:107], v[228:231], v[44:47], v[8:11]
	v_mfma_f32_16x16x32_bf16 v[8:11], v[232:235], v[40:43], v[12:15]
	v_mfma_f32_16x16x32_bf16 v[108:111], v[236:239], v[44:47], v[8:11]
	v_mfma_f32_16x16x32_bf16 v[8:11], v[198:201], v[76:79], v[204:207]
	v_mfma_f32_16x16x32_bf16 v[72:75], v[228:231], v[176:179], v[8:11]
	v_mfma_f32_16x16x32_bf16 v[8:11], v[232:235], v[76:79], v[208:211]
	v_mfma_f32_16x16x32_bf16 v[76:79], v[236:239], v[176:179], v[8:11]
	v_mfma_f32_16x16x32_bf16 v[8:11], v[198:201], v[180:183], v[220:223]
	v_mfma_f32_16x16x32_bf16 v[40:43], v[228:231], v[186:189], v[8:11]
	v_mfma_f32_16x16x32_bf16 v[8:11], v[232:235], v[180:183], v[190:193]
	v_mfma_f32_16x16x32_bf16 v[44:47], v[236:239], v[186:189], v[8:11]
	v_mfma_f32_16x16x32_bf16 v[8:11], v[198:201], v[212:215], v[224:227]
	v_mfma_f32_16x16x32_bf16 v[12:15], v[232:235], v[212:215], v[168:171]
	v_mfma_f32_16x16x32_bf16 v[8:11], v[228:231], v[216:219], v[8:11]
	v_mfma_f32_16x16x32_bf16 v[12:15], v[236:239], v[216:219], v[12:15]
	s_setprio 0
	s_barrier
	s_andn2_b64 vcc, exec, s[84:85]
	s_cbranch_vccnz .LBB0_490
	s_barrier

; #define PG8_STAGE(bufoff, gbase, voff) do { unsigned long long _gb = (unsigned long long)(gbase); asm volatile("" : "+s"(_gb)); _Pragma("unroll") for (int _i = 0; _i < 2; ++_i) \
;         __builtin_amdgcn_global_load_lds((const GAS unsigned*)((const GAS char*)_gb + (voff)[_i]), (LAS unsigned*)(lds + (bufoff) + ldsw + _i * 8192), 16, 0, 0); } while (0)
; #define PG8_LDA(dst, b, h) do { _Pragma("unroll") for (int m = 0; m < 4; ++m) _Pragma("unroll") for (int k = 0; k < 2; ++k) dst[m][k] = *(const LAS bf16x8*)(lds + PG8_SA(b, h) + aoff + m * 2048 + k * 1024); } while (0)
; #define PG8_LDB(dst, b, h) do { _Pragma("unroll") for (int n = 0; n < 2; ++n) _Pragma("unroll") for (int k = 0; k < 2; ++k) dst[n][k] = *(const LAS bf16x8*)(lds + PG8_SB(b, h) + boff + n * 2048 + k * 1024); } while (0)
; #define PG8_MMA(ai, bj, At, Bt) do { __builtin_amdgcn_s_setprio(1); _Pragma("unroll") for (int m = 0; m < 4; ++m) _Pragma("unroll") for (int n = 0; n < 2; ++n) _Pragma("unroll") for (int k = 0; k < 2; ++k) \
;         acc[ai][bj][m][n] = __builtin_amdgcn_mfma_f32_16x16x32_bf16(Bt[n][k], At[m][k], acc[ai][bj][m][n], 0, 0, 0); __builtin_amdgcn_s_setprio(0); } while (0)
; template <class Epi, bool ALIGN_EPI>
; __device__ __forceinline__ void gemm_phase(LAS unsigned char* lds, const Gemm g, const StaticOrder& S, const Epi& E, const int wid) {
;     ...
;         const char* nA = has_next ? (const char*)g.A + (size_t)nxt.pm * tstep : cA; const char* nB = has_next ? (const char*)g.Bt + (size_t)nxt.pn * tstep : cB;
;         for (int t = 0; t < nt; t += 2) {
;             const bool last = (t == nt - 2);
;             const char* a1 = cA + (size_t)(t + 1) * kstep;
;             const char* a2 = last ? nA : cA + (size_t)(t + 2) * kstep; const char* b2 = last ? nB : cB + (size_t)(t + 2) * kstep;
;             const char* a3 = a2 + kstep; const char* b3 = b2 + kstep;
;             PG8_LDB(B0, 0, 0); PG8_LDB(B1, 0, 1); PG8_SCHED; PG8_LDA(At, 0, 0); PG8_STAGE(PG8_SA(1, 1), a1 + hstep, voffA);
;             PG8_WAIT_V(8); PG8_WAIT_L(0); PG8_BAR; PG8_MMA(0, 0, At, B0); PG8_MMA(0, 1, At, B1); PG8_BAR; PG8_SCHED;
;             PG8_LDA(At, 0, 1); PG8_STAGE(PG8_SB(0, 0), b2, voffB); PG8_STAGE(PG8_SB(0, 1), b2 + hstepB, voffB); PG8_STAGE(PG8_SA(0, 0), a2, voffA);
;             PG8_WAIT_V(8); PG8_WAIT_L(0); PG8_BAR; PG8_MMA(1, 0, At, B0); PG8_MMA(1, 1, At, B1); PG8_BAR; PG8_SCHED;
.LBB0_722:
	ds_read_b128 v[128:131], v203
	ds_read_b128 v[132:135], v203 offset:1024
	ds_read_b128 v[136:139], v203 offset:2048
	ds_read_b128 v[140:143], v203 offset:3072
	ds_read_b128 v[144:147], v204
	ds_read_b128 v[148:151], v204 offset:1024
	ds_read_b128 v[152:155], v204 offset:2048
	ds_read_b128 v[156:159], v204 offset:3072
	s_cmp_eq_u32 s52, 28
	s_cselect_b32 s30, s21, s50
	s_cselect_b32 s31, s15, s51
	s_cselect_b32 s28, s47, s48
	s_cselect_b32 s29, s13, s49
	s_add_u32 s26, s30, 0x80
	s_addc_u32 s27, s31, 0
	s_mov_b64 s[54:55], s[24:25]
	ds_read_b128 v[160:163], v205
	ds_read_b128 v[164:167], v205 offset:1024
	ds_read_b128 v[168:171], v205 offset:2048
	ds_read_b128 v[172:175], v205 offset:3072
	ds_read_b128 v[188:191], v205 offset:4096
	ds_read_b128 v[192:195], v205 offset:5120
	ds_read_b128 v[196:199], v205 offset:6144
	s_add_i32 m0, s23, 0xc000
	ds_read_b128 v[206:209], v205 offset:7168
	global_load_lds_dwordx4 v176, s[54:55]
	s_add_i32 m0, s23, 0xe000
	s_nop 0
	global_load_lds_dwordx4 v180, s[54:55]
	s_waitcnt vmcnt(8) lgkmcnt(0)
	s_barrier
	s_setprio 1
	v_mfma_f32_16x16x32_bf16 v[124:127], v[128:131], v[160:163], v[124:127]
	v_mfma_f32_16x16x32_bf16 v[120:123], v[136:139], v[160:163], v[120:123]
	v_mfma_f32_16x16x32_bf16 v[108:111], v[128:131], v[168:171], v[108:111]
	v_mfma_f32_16x16x32_bf16 v[104:107], v[136:139], v[168:171], v[104:107]
	v_mfma_f32_16x16x32_bf16 v[92:95], v[128:131], v[188:191], v[92:95]
	v_mfma_f32_16x16x32_bf16 v[88:91], v[136:139], v[188:191], v[88:91]
	v_mfma_f32_16x16x32_bf16 v[76:79], v[128:131], v[196:199], v[76:79]
	v_mfma_f32_16x16x32_bf16 v[72:75], v[136:139], v[196:199], v[72:75]
	v_mfma_f32_16x16x32_bf16 v[124:127], v[132:135], v[164:167], v[124:127]
	v_mfma_f32_16x16x32_bf16 v[120:123], v[140:143], v[164:167], v[120:123]
	v_mfma_f32_16x16x32_bf16 v[108:111], v[132:135], v[172:175], v[108:111]
	v_mfma_f32_16x16x32_bf16 v[104:107], v[140:143], v[172:175], v[104:107]
	v_mfma_f32_16x16x32_bf16 v[92:95], v[132:135], v[192:195], v[92:95]
	v_mfma_f32_16x16x32_bf16 v[88:91], v[140:143], v[192:195], v[88:91]
	v_mfma_f32_16x16x32_bf16 v[76:79], v[132:135], v[206:209], v[76:79]
	v_mfma_f32_16x16x32_bf16 v[72:75], v[140:143], v[206:209], v[72:75]
	v_mfma_f32_16x16x32_bf16 v[116:119], v[144:147], v[160:163], v[116:119]
	v_mfma_f32_16x16x32_bf16 v[112:115], v[152:155], v[160:163], v[112:115]
	v_mfma_f32_16x16x32_bf16 v[100:103], v[144:147], v[168:171], v[100:103]
	v_mfma_f32_16x16x32_bf16 v[96:99], v[152:155], v[168:171], v[96:99]
	v_mfma_f32_16x16x32_bf16 v[84:87], v[144:147], v[188:191], v[84:87]
	v_mfma_f32_16x16x32_bf16 v[80:83], v[152:155], v[188:191], v[80:83]
	v_mfma_f32_16x16x32_bf16 v[68:71], v[144:147], v[196:199], v[68:71]
	v_mfma_f32_16x16x32_bf16 v[64:67], v[152:155], v[196:199], v[64:67]
	v_mfma_f32_16x16x32_bf16 v[116:119], v[148:151], v[164:167], v[116:119]
	v_mfma_f32_16x16x32_bf16 v[112:115], v[156:159], v[164:167], v[112:115]
	v_mfma_f32_16x16x32_bf16 v[100:103], v[148:151], v[172:175], v[100:103]
	v_mfma_f32_16x16x32_bf16 v[96:99], v[156:159], v[172:175], v[96:99]
	v_mfma_f32_16x16x32_bf16 v[84:87], v[148:151], v[192:195], v[84:87]
	v_mfma_f32_16x16x32_bf16 v[80:83], v[156:159], v[192:195], v[80:83]
	v_mfma_f32_16x16x32_bf16 v[68:71], v[148:151], v[206:209], v[68:71]
	v_mfma_f32_16x16x32_bf16 v[64:67], v[156:159], v[206:209], v[64:67]
	s_setprio 0
	s_barrier
	s_mov_b64 s[54:55], s[28:29]
	s_add_i32 s53, s45, s33
	ds_read_b128 v[160:163], v205 offset:16384
	ds_read_b128 v[164:167], v205 offset:17408
	ds_read_b128 v[168:171], v205 offset:18432
	ds_read_b128 v[172:175], v205 offset:19456
	ds_read_b128 v[188:191], v205 offset:20480
	ds_read_b128 v[192:195], v205 offset:21504
	ds_read_b128 v[196:199], v205 offset:22528
	s_mov_b32 m0, s53
	ds_read_b128 v[206:209], v205 offset:23552
	global_load_lds_dwordx4 v178, s[54:55]
	s_add_i32 m0, s53, 0x2000
	s_nop 0
	global_load_lds_dwordx4 v182, s[54:55]
	s_add_u32 s54, s28, 0x20000
	s_addc_u32 s55, s29, 0
	s_add_i32 s53, s46, s33
	s_mov_b32 m0, s53
	s_nop 0
	global_load_lds_dwordx4 v178, s[54:55]
	s_add_i32 m0, s53, 0x2000
	s_nop 0
	global_load_lds_dwordx4 v182, s[54:55]
	s_mov_b32 m0, s23
	s_mov_b64 s[54:55], s[30:31]
	global_load_lds_dwordx4 v176, s[54:55]
	s_mov_b32 m0, s38
	s_nop 0
	global_load_lds_dwordx4 v180, s[54:55]
	s_waitcnt vmcnt(8) lgkmcnt(0)
	s_barrier
	s_setprio 1
	v_mfma_f32_16x16x32_bf16 v[60:63], v[128:131], v[160:163], v[60:63]
	v_mfma_f32_16x16x32_bf16 v[56:59], v[136:139], v[160:163], v[56:59]
	v_mfma_f32_16x16x32_bf16 v[44:47], v[128:131], v[168:171], v[44:47]
	v_mfma_f32_16x16x32_bf16 v[40:43], v[136:139], v[168:171], v[40:43]
	v_mfma_f32_16x16x32_bf16 v[28:31], v[128:131], v[188:191], v[28:31]
	v_mfma_f32_16x16x32_bf16 v[24:27], v[136:139], v[188:191], v[24:27]
	v_mfma_f32_16x16x32_bf16 v[12:15], v[128:131], v[196:199], v[12:15]
	v_mfma_f32_16x16x32_bf16 v[8:11], v[136:139], v[196:199], v[8:11]
	v_mfma_f32_16x16x32_bf16 v[60:63], v[132:135], v[164:167], v[60:63]
	v_mfma_f32_16x16x32_bf16 v[56:59], v[140:143], v[164:167], v[56:59]
	v_mfma_f32_16x16x32_bf16 v[44:47], v[132:135], v[172:175], v[44:47]
	v_mfma_f32_16x16x32_bf16 v[40:43], v[140:143], v[172:175], v[40:43]
	v_mfma_f32_16x16x32_bf16 v[28:31], v[132:135], v[192:195], v[28:31]
	v_mfma_f32_16x16x32_bf16 v[24:27], v[140:143], v[192:195], v[24:27]
	v_mfma_f32_16x16x32_bf16 v[12:15], v[132:135], v[206:209], v[12:15]
	v_mfma_f32_16x16x32_bf16 v[8:11], v[140:143], v[206:209], v[8:11]
	v_mfma_f32_16x16x32_bf16 v[52:55], v[144:147], v[160:163], v[52:55]
	v_mfma_f32_16x16x32_bf16 v[48:51], v[152:155], v[160:163], v[48:51]
	v_mfma_f32_16x16x32_bf16 v[36:39], v[144:147], v[168:171], v[36:39]
	v_mfma_f32_16x16x32_bf16 v[32:35], v[152:155], v[168:171], v[32:35]
	v_mfma_f32_16x16x32_bf16 v[20:23], v[144:147], v[188:191], v[20:23]
	v_mfma_f32_16x16x32_bf16 v[16:19], v[152:155], v[188:191], v[16:19]
	v_mfma_f32_16x16x32_bf16 v[4:7], v[144:147], v[196:199], v[4:7]
	v_mfma_f32_16x16x32_bf16 v[0:3], v[152:155], v[196:199], v[0:3]
	v_mfma_f32_16x16x32_bf16 v[52:55], v[148:151], v[164:167], v[52:55]
	v_mfma_f32_16x16x32_bf16 v[48:51], v[156:159], v[164:167], v[48:51]
	v_mfma_f32_16x16x32_bf16 v[36:39], v[148:151], v[172:175], v[36:39]
	v_mfma_f32_16x16x32_bf16 v[32:35], v[156:159], v[172:175], v[32:35]
	v_mfma_f32_16x16x32_bf16 v[20:23], v[148:151], v[192:195], v[20:23]
	v_mfma_f32_16x16x32_bf16 v[16:19], v[156:159], v[192:195], v[16:19]
	v_mfma_f32_16x16x32_bf16 v[4:7], v[148:151], v[206:209], v[4:7]
	v_mfma_f32_16x16x32_bf16 v[0:3], v[156:159], v[206:209], v[0:3]
	s_setprio 0
	s_barrier
; #define PG8_STAGE(bufoff, gbase, voff) do { unsigned long long _gb = (unsigned long long)(gbase); asm volatile("" : "+s"(_gb)); _Pragma("unroll") for (int _i = 0; _i < 2; ++_i) \
;         __builtin_amdgcn_global_load_lds((const GAS unsigned*)((const GAS char*)_gb + (voff)[_i]), (LAS unsigned*)(lds + (bufoff) + ldsw + _i * 8192), 16, 0, 0); } while (0)
; #define PG8_LDA(dst, b, h) do { _Pragma("unroll") for (int m = 0; m < 4; ++m) _Pragma("unroll") for (int k = 0; k < 2; ++k) dst[m][k] = *(const LAS bf16x8*)(lds + PG8_SA(b, h) + aoff + m * 2048 + k * 1024); } while (0)
; #define PG8_LDB(dst, b, h) do { _Pragma("unroll") for (int n = 0; n < 2; ++n) _Pragma("unroll") for (int k = 0; k < 2; ++k) dst[n][k] = *(const LAS bf16x8*)(lds + PG8_SB(b, h) + boff + n * 2048 + k * 1024); } while (0)
; #define PG8_MMA(ai, bj, At, Bt) do { __builtin_amdgcn_s_setprio(1); _Pragma("unroll") for (int m = 0; m < 4; ++m) _Pragma("unroll") for (int n = 0; n < 2; ++n) _Pragma("unroll") for (int k = 0; k < 2; ++k) \
;         acc[ai][bj][m][n] = __builtin_amdgcn_mfma_f32_16x16x32_bf16(Bt[n][k], At[m][k], acc[ai][bj][m][n], 0, 0, 0); __builtin_amdgcn_s_setprio(0); } while (0)
; #define PG8_WAIT_V(n) asm volatile("s_waitcnt vmcnt(" #n ")" ::: "memory")
; #define PG8_WAIT_L(n) asm volatile("s_waitcnt lgkmcnt(" #n ")" ::: "memory")
; #define PG8_BAR __builtin_amdgcn_s_barrier()
; #define PG8_SCHED __builtin_amdgcn_sched_barrier(0)
; template <class Epi, bool ALIGN_EPI>
; __device__ __forceinline__ void gemm_phase(LAS unsigned char* lds, const Gemm g, const StaticOrder& S, const Epi& E, const int wid) {
;     ...
;             PG8_LDB(B0, 1, 0); PG8_LDB(B1, 1, 1); PG8_SCHED; PG8_LDA(At, 1, 0); PG8_STAGE(PG8_SA(0, 1), a2 + hstep, voffA);
;             PG8_WAIT_V(8); PG8_WAIT_L(0); PG8_BAR; PG8_MMA(0, 0, At, B0); PG8_MMA(0, 1, At, B1); PG8_BAR; PG8_SCHED;
;             PG8_LDA(At, 1, 1); PG8_STAGE(PG8_SB(1, 0), b3, voffB); PG8_STAGE(PG8_SB(1, 1), b3 + hstepB, voffB); PG8_STAGE(PG8_SA(1, 0), a3, voffA);
;             PG8_WAIT_V(8); PG8_WAIT_L(0); PG8_BAR; PG8_MMA(1, 0, At, B0); PG8_MMA(1, 1, At, B1); PG8_BAR; PG8_SCHED;
;         }
;         if constexpr (ALIGN_EPI) { if (wr == 0) PG8_BAR; }
	s_add_i32 s53, 0, 0x18000
	s_add_i32 s54, 0, 0x1c000
	v_add_u32_e32 v140, s53, v201
	v_add_u32_e32 v156, s54, v201
	ds_read_b128 v[128:131], v140
	ds_read_b128 v[132:135], v140 offset:1024
	ds_read_b128 v[136:139], v140 offset:2048
	ds_read_b128 v[140:143], v140 offset:3072
	ds_read_b128 v[144:147], v156
	ds_read_b128 v[148:151], v156 offset:1024
	ds_read_b128 v[152:155], v156 offset:2048
	ds_read_b128 v[156:159], v156 offset:3072
	s_add_u32 s30, s30, 0x80000
	s_addc_u32 s31, s31, 0
	s_mov_b32 m0, s39
	ds_read_b128 v[160:163], v205 offset:32768
	ds_read_b128 v[164:167], v205 offset:33792
	ds_read_b128 v[168:171], v205 offset:34816
	ds_read_b128 v[172:175], v205 offset:35840
	ds_read_b128 v[188:191], v205 offset:36864
	ds_read_b128 v[192:195], v205 offset:37888
	ds_read_b128 v[196:199], v205 offset:38912
	ds_read_b128 v[206:209], v205 offset:39936
	s_nop 0
	global_load_lds_dwordx4 v176, s[30:31]
	s_mov_b32 m0, s40
	s_nop 0
	global_load_lds_dwordx4 v180, s[30:31]
	s_waitcnt vmcnt(8) lgkmcnt(0)
	s_barrier
	s_setprio 1
	v_mfma_f32_16x16x32_bf16 v[124:127], v[128:131], v[160:163], v[124:127]
	v_mfma_f32_16x16x32_bf16 v[120:123], v[136:139], v[160:163], v[120:123]
	v_mfma_f32_16x16x32_bf16 v[108:111], v[128:131], v[168:171], v[108:111]
	v_mfma_f32_16x16x32_bf16 v[104:107], v[136:139], v[168:171], v[104:107]
	v_mfma_f32_16x16x32_bf16 v[92:95], v[128:131], v[188:191], v[92:95]
	v_mfma_f32_16x16x32_bf16 v[88:91], v[136:139], v[188:191], v[88:91]
	v_mfma_f32_16x16x32_bf16 v[76:79], v[128:131], v[196:199], v[76:79]
	v_mfma_f32_16x16x32_bf16 v[72:75], v[136:139], v[196:199], v[72:75]
	v_mfma_f32_16x16x32_bf16 v[124:127], v[132:135], v[164:167], v[124:127]
	v_mfma_f32_16x16x32_bf16 v[120:123], v[140:143], v[164:167], v[120:123]
	v_mfma_f32_16x16x32_bf16 v[108:111], v[132:135], v[172:175], v[108:111]
	v_mfma_f32_16x16x32_bf16 v[104:107], v[140:143], v[172:175], v[104:107]
	v_mfma_f32_16x16x32_bf16 v[92:95], v[132:135], v[192:195], v[92:95]
	v_mfma_f32_16x16x32_bf16 v[88:91], v[140:143], v[192:195], v[88:91]
	v_mfma_f32_16x16x32_bf16 v[76:79], v[132:135], v[206:209], v[76:79]
	v_mfma_f32_16x16x32_bf16 v[72:75], v[140:143], v[206:209], v[72:75]
	v_mfma_f32_16x16x32_bf16 v[116:119], v[144:147], v[160:163], v[116:119]
	v_mfma_f32_16x16x32_bf16 v[112:115], v[152:155], v[160:163], v[112:115]
	v_mfma_f32_16x16x32_bf16 v[100:103], v[144:147], v[168:171], v[100:103]
	v_mfma_f32_16x16x32_bf16 v[96:99], v[152:155], v[168:171], v[96:99]
	v_mfma_f32_16x16x32_bf16 v[84:87], v[144:147], v[188:191], v[84:87]
	v_mfma_f32_16x16x32_bf16 v[80:83], v[152:155], v[188:191], v[80:83]
	v_mfma_f32_16x16x32_bf16 v[68:71], v[144:147], v[196:199], v[68:71]
	v_mfma_f32_16x16x32_bf16 v[64:67], v[152:155], v[196:199], v[64:67]
	v_mfma_f32_16x16x32_bf16 v[116:119], v[148:151], v[164:167], v[116:119]
	v_mfma_f32_16x16x32_bf16 v[112:115], v[156:159], v[164:167], v[112:115]
	v_mfma_f32_16x16x32_bf16 v[100:103], v[148:151], v[172:175], v[100:103]
	v_mfma_f32_16x16x32_bf16 v[96:99], v[156:159], v[172:175], v[96:99]
	v_mfma_f32_16x16x32_bf16 v[84:87], v[148:151], v[192:195], v[84:87]
	v_mfma_f32_16x16x32_bf16 v[80:83], v[156:159], v[192:195], v[80:83]
	v_mfma_f32_16x16x32_bf16 v[68:71], v[148:151], v[206:209], v[68:71]
	v_mfma_f32_16x16x32_bf16 v[64:67], v[156:159], v[206:209], v[64:67]
	s_setprio 0
	s_barrier
	s_add_u32 s30, s28, 0x80
	s_addc_u32 s31, s29, 0
	s_add_i32 s53, s53, s33
	ds_read_b128 v[160:163], v205 offset:49152
	ds_read_b128 v[164:167], v205 offset:50176
	ds_read_b128 v[168:171], v205 offset:51200
	ds_read_b128 v[172:175], v205 offset:52224
	ds_read_b128 v[188:191], v205 offset:53248
	ds_read_b128 v[192:195], v205 offset:54272
	ds_read_b128 v[196:199], v205 offset:55296
	s_mov_b32 m0, s53
	ds_read_b128 v[206:209], v205 offset:56320
	global_load_lds_dwordx4 v178, s[30:31]
	s_add_i32 m0, s53, 0x2000
	s_add_u32 s28, s28, 0x20080
	s_addc_u32 s29, s29, 0
	global_load_lds_dwordx4 v182, s[30:31]
	s_add_i32 s30, s54, s33
	s_mov_b32 m0, s30
	s_nop 0
	global_load_lds_dwordx4 v178, s[28:29]
	s_add_i32 m0, s30, 0x2000
	s_nop 0
	global_load_lds_dwordx4 v182, s[28:29]
	s_mov_b32 m0, s42
	s_nop 0
	global_load_lds_dwordx4 v176, s[26:27]
	s_mov_b32 m0, s43
	s_nop 0
	global_load_lds_dwordx4 v180, s[26:27]
	s_waitcnt vmcnt(8) lgkmcnt(0)
	s_barrier
	s_setprio 1
	v_mfma_f32_16x16x32_bf16 v[60:63], v[128:131], v[160:163], v[60:63]
	v_mfma_f32_16x16x32_bf16 v[56:59], v[136:139], v[160:163], v[56:59]
	v_mfma_f32_16x16x32_bf16 v[44:47], v[128:131], v[168:171], v[44:47]
	v_mfma_f32_16x16x32_bf16 v[40:43], v[136:139], v[168:171], v[40:43]
	v_mfma_f32_16x16x32_bf16 v[28:31], v[128:131], v[188:191], v[28:31]
	v_mfma_f32_16x16x32_bf16 v[24:27], v[136:139], v[188:191], v[24:27]
	v_mfma_f32_16x16x32_bf16 v[12:15], v[128:131], v[196:199], v[12:15]
	v_mfma_f32_16x16x32_bf16 v[8:11], v[136:139], v[196:199], v[8:11]
	v_mfma_f32_16x16x32_bf16 v[60:63], v[132:135], v[164:167], v[60:63]
	v_mfma_f32_16x16x32_bf16 v[56:59], v[140:143], v[164:167], v[56:59]
	v_mfma_f32_16x16x32_bf16 v[44:47], v[132:135], v[172:175], v[44:47]
	v_mfma_f32_16x16x32_bf16 v[40:43], v[140:143], v[172:175], v[40:43]
	v_mfma_f32_16x16x32_bf16 v[28:31], v[132:135], v[192:195], v[28:31]
	v_mfma_f32_16x16x32_bf16 v[24:27], v[140:143], v[192:195], v[24:27]
	v_mfma_f32_16x16x32_bf16 v[12:15], v[132:135], v[206:209], v[12:15]
	v_mfma_f32_16x16x32_bf16 v[8:11], v[140:143], v[206:209], v[8:11]
	v_mfma_f32_16x16x32_bf16 v[52:55], v[144:147], v[160:163], v[52:55]
	v_mfma_f32_16x16x32_bf16 v[48:51], v[152:155], v[160:163], v[48:51]
	v_mfma_f32_16x16x32_bf16 v[36:39], v[144:147], v[168:171], v[36:39]
	v_mfma_f32_16x16x32_bf16 v[32:35], v[152:155], v[168:171], v[32:35]
	v_mfma_f32_16x16x32_bf16 v[20:23], v[144:147], v[188:191], v[20:23]
	v_mfma_f32_16x16x32_bf16 v[16:19], v[152:155], v[188:191], v[16:19]
	v_mfma_f32_16x16x32_bf16 v[4:7], v[144:147], v[196:199], v[4:7]
	v_mfma_f32_16x16x32_bf16 v[0:3], v[152:155], v[196:199], v[0:3]
	v_mfma_f32_16x16x32_bf16 v[52:55], v[148:151], v[164:167], v[52:55]
	v_mfma_f32_16x16x32_bf16 v[48:51], v[156:159], v[164:167], v[48:51]
	v_mfma_f32_16x16x32_bf16 v[36:39], v[148:151], v[172:175], v[36:39]
	v_mfma_f32_16x16x32_bf16 v[32:35], v[156:159], v[172:175], v[32:35]
	v_mfma_f32_16x16x32_bf16 v[20:23], v[148:151], v[192:195], v[20:23]
	v_mfma_f32_16x16x32_bf16 v[16:19], v[156:159], v[192:195], v[16:19]
	v_mfma_f32_16x16x32_bf16 v[4:7], v[148:151], v[206:209], v[4:7]
	v_mfma_f32_16x16x32_bf16 v[0:3], v[156:159], v[206:209], v[0:3]
	s_setprio 0
	s_barrier
	s_add_i32 s52, s52, 2
	s_add_u32 s48, s48, 0x100
	s_addc_u32 s49, s49, 0
	s_add_u32 s24, s24, 0x100
	s_addc_u32 s25, s25, 0
	s_add_u32 s50, s50, 0x100
	s_addc_u32 s51, s51, 0
	s_cmp_gt_u32 s52, 29
	s_cbranch_scc0 .LBB0_722
	s_and_b64 vcc, exec, s[84:85]
	s_cbranch_vccz .LBB0_725
	s_barrier

; #define PG8_STAGE(bufoff, gbase, voff) do { unsigned long long _gb = (unsigned long long)(gbase); asm volatile("" : "+s"(_gb)); _Pragma("unroll") for (int _i = 0; _i < 2; ++_i) \
;         __builtin_amdgcn_global_load_lds((const GAS unsigned*)((const GAS char*)_gb + (voff)[_i]), (LAS unsigned*)(lds + (bufoff) + ldsw + _i * 8192), 16, 0, 0); } while (0)
; #define PG8_LDA(dst, b, h) do { _Pragma("unroll") for (int m = 0; m < 4; ++m) _Pragma("unroll") for (int k = 0; k < 2; ++k) dst[m][k] = *(const LAS bf16x8*)(lds + PG8_SA(b, h) + aoff + m * 2048 + k * 1024); } while (0)
; #define PG8_LDB(dst, b, h) do { _Pragma("unroll") for (int n = 0; n < 2; ++n) _Pragma("unroll") for (int k = 0; k < 2; ++k) dst[n][k] = *(const LAS bf16x8*)(lds + PG8_SB(b, h) + boff + n * 2048 + k * 1024); } while (0)
; #define PG8_MMA(ai, bj, At, Bt) do { __builtin_amdgcn_s_setprio(1); _Pragma("unroll") for (int m = 0; m < 4; ++m) _Pragma("unroll") for (int n = 0; n < 2; ++n) _Pragma("unroll") for (int k = 0; k < 2; ++k) \
;         acc[ai][bj][m][n] = __builtin_amdgcn_mfma_f32_16x16x32_bf16(Bt[n][k], At[m][k], acc[ai][bj][m][n], 0, 0, 0); __builtin_amdgcn_s_setprio(0); } while (0)
; template <class Epi, bool ALIGN_EPI>
; __device__ __forceinline__ void gemm_phase(LAS unsigned char* lds, const Gemm g, const StaticOrder& S, const Epi& E, const int wid) {
;     ...
;         const char* nA = has_next ? (const char*)g.A + (size_t)nxt.pm * tstep : cA; const char* nB = has_next ? (const char*)g.Bt + (size_t)nxt.pn * tstep : cB;
;         for (int t = 0; t < nt; t += 2) {
;             const bool last = (t == nt - 2);
;             const char* a1 = cA + (size_t)(t + 1) * kstep;
;             const char* a2 = last ? nA : cA + (size_t)(t + 2) * kstep; const char* b2 = last ? nB : cB + (size_t)(t + 2) * kstep;
;             const char* a3 = a2 + kstep; const char* b3 = b2 + kstep;
;             PG8_LDB(B0, 0, 0); PG8_LDB(B1, 0, 1); PG8_SCHED; PG8_LDA(At, 0, 0); PG8_STAGE(PG8_SA(1, 1), a1 + hstep, voffA);
;             PG8_WAIT_V(8); PG8_WAIT_L(0); PG8_BAR; PG8_MMA(0, 0, At, B0); PG8_MMA(0, 1, At, B1); PG8_BAR; PG8_SCHED;
;             PG8_LDA(At, 0, 1); PG8_STAGE(PG8_SB(0, 0), b2, voffB); PG8_STAGE(PG8_SB(0, 1), b2 + hstepB, voffB); PG8_STAGE(PG8_SA(0, 0), a2, voffA);
;             PG8_WAIT_V(8); PG8_WAIT_L(0); PG8_BAR; PG8_MMA(1, 0, At, B0); PG8_MMA(1, 1, At, B1); PG8_BAR; PG8_SCHED;
.LBB0_811:
	ds_read_b128 v[128:131], v202
	ds_read_b128 v[132:135], v202 offset:1024
	ds_read_b128 v[136:139], v202 offset:2048
	ds_read_b128 v[140:143], v202 offset:3072
	ds_read_b128 v[144:147], v203
	ds_read_b128 v[148:151], v203 offset:1024
	ds_read_b128 v[152:155], v203 offset:2048
	ds_read_b128 v[156:159], v203 offset:3072
	s_cmp_eq_u32 s49, 28
	s_cselect_b32 s24, s43, s47
	s_cselect_b32 s25, s13, s48
	s_cselect_b32 s22, s44, s45
	s_cselect_b32 s23, s11, s46
	s_add_u32 s20, s24, 0x80
	s_addc_u32 s21, s25, 0
	s_mov_b64 s[50:51], s[18:19]
	ds_read_b128 v[160:163], v204
	ds_read_b128 v[164:167], v204 offset:1024
	ds_read_b128 v[168:171], v204 offset:2048
	ds_read_b128 v[172:175], v204 offset:3072
	ds_read_b128 v[188:191], v204 offset:4096
	ds_read_b128 v[192:195], v204 offset:5120
	ds_read_b128 v[196:199], v204 offset:6144
	s_add_i32 m0, s28, 0xc000
	ds_read_b128 v[206:209], v204 offset:7168
	global_load_lds_dwordx4 v182, s[50:51]
	s_add_i32 m0, s28, 0xe000
	s_nop 0
	global_load_lds_dwordx4 v178, s[50:51]
	s_waitcnt vmcnt(8) lgkmcnt(0)
	s_barrier
	s_setprio 1
	v_mfma_f32_16x16x32_bf16 v[124:127], v[128:131], v[160:163], v[124:127]
	v_mfma_f32_16x16x32_bf16 v[120:123], v[136:139], v[160:163], v[120:123]
	v_mfma_f32_16x16x32_bf16 v[108:111], v[128:131], v[168:171], v[108:111]
	v_mfma_f32_16x16x32_bf16 v[104:107], v[136:139], v[168:171], v[104:107]
	v_mfma_f32_16x16x32_bf16 v[92:95], v[128:131], v[188:191], v[92:95]
	v_mfma_f32_16x16x32_bf16 v[88:91], v[136:139], v[188:191], v[88:91]
	v_mfma_f32_16x16x32_bf16 v[76:79], v[128:131], v[196:199], v[76:79]
	v_mfma_f32_16x16x32_bf16 v[72:75], v[136:139], v[196:199], v[72:75]
	v_mfma_f32_16x16x32_bf16 v[124:127], v[132:135], v[164:167], v[124:127]
	v_mfma_f32_16x16x32_bf16 v[120:123], v[140:143], v[164:167], v[120:123]
	v_mfma_f32_16x16x32_bf16 v[108:111], v[132:135], v[172:175], v[108:111]
	v_mfma_f32_16x16x32_bf16 v[104:107], v[140:143], v[172:175], v[104:107]
	v_mfma_f32_16x16x32_bf16 v[92:95], v[132:135], v[192:195], v[92:95]
	v_mfma_f32_16x16x32_bf16 v[88:91], v[140:143], v[192:195], v[88:91]
	v_mfma_f32_16x16x32_bf16 v[76:79], v[132:135], v[206:209], v[76:79]
	v_mfma_f32_16x16x32_bf16 v[72:75], v[140:143], v[206:209], v[72:75]
	v_mfma_f32_16x16x32_bf16 v[116:119], v[144:147], v[160:163], v[116:119]
	v_mfma_f32_16x16x32_bf16 v[112:115], v[152:155], v[160:163], v[112:115]
	v_mfma_f32_16x16x32_bf16 v[100:103], v[144:147], v[168:171], v[100:103]
	v_mfma_f32_16x16x32_bf16 v[96:99], v[152:155], v[168:171], v[96:99]
	v_mfma_f32_16x16x32_bf16 v[84:87], v[144:147], v[188:191], v[84:87]
	v_mfma_f32_16x16x32_bf16 v[80:83], v[152:155], v[188:191], v[80:83]
	v_mfma_f32_16x16x32_bf16 v[68:71], v[144:147], v[196:199], v[68:71]
	v_mfma_f32_16x16x32_bf16 v[64:67], v[152:155], v[196:199], v[64:67]
	v_mfma_f32_16x16x32_bf16 v[116:119], v[148:151], v[164:167], v[116:119]
	v_mfma_f32_16x16x32_bf16 v[112:115], v[156:159], v[164:167], v[112:115]
	v_mfma_f32_16x16x32_bf16 v[100:103], v[148:151], v[172:175], v[100:103]
	v_mfma_f32_16x16x32_bf16 v[96:99], v[156:159], v[172:175], v[96:99]
	v_mfma_f32_16x16x32_bf16 v[84:87], v[148:151], v[192:195], v[84:87]
	v_mfma_f32_16x16x32_bf16 v[80:83], v[156:159], v[192:195], v[80:83]
	v_mfma_f32_16x16x32_bf16 v[68:71], v[148:151], v[206:209], v[68:71]
	v_mfma_f32_16x16x32_bf16 v[64:67], v[156:159], v[206:209], v[64:67]
	s_setprio 0
	s_barrier
	s_mov_b64 s[50:51], s[22:23]
	s_add_i32 s52, s38, s33
	ds_read_b128 v[160:163], v204 offset:16384
	ds_read_b128 v[164:167], v204 offset:17408
	ds_read_b128 v[168:171], v204 offset:18432
	ds_read_b128 v[172:175], v204 offset:19456
	ds_read_b128 v[188:191], v204 offset:20480
	ds_read_b128 v[192:195], v204 offset:21504
	ds_read_b128 v[196:199], v204 offset:22528
	s_mov_b32 m0, s52
	ds_read_b128 v[206:209], v204 offset:23552
	global_load_lds_dwordx4 v180, s[50:51]
	s_add_i32 m0, s52, 0x2000
	s_nop 0
	global_load_lds_dwordx4 v176, s[50:51]
	s_add_u32 s50, s22, 0x20000
	s_addc_u32 s51, s23, 0
	s_add_i32 s52, s39, s33
	s_mov_b32 m0, s52
	s_nop 0
	global_load_lds_dwordx4 v180, s[50:51]
	s_add_i32 m0, s52, 0x2000
	s_nop 0
	global_load_lds_dwordx4 v176, s[50:51]
	s_mov_b32 m0, s28
	s_mov_b64 s[50:51], s[24:25]
	global_load_lds_dwordx4 v182, s[50:51]
	s_mov_b32 m0, s29
	s_nop 0
	global_load_lds_dwordx4 v178, s[50:51]
	s_waitcnt vmcnt(8) lgkmcnt(0)
	s_barrier
	s_setprio 1
	v_mfma_f32_16x16x32_bf16 v[60:63], v[128:131], v[160:163], v[60:63]
	v_mfma_f32_16x16x32_bf16 v[56:59], v[136:139], v[160:163], v[56:59]
	v_mfma_f32_16x16x32_bf16 v[44:47], v[128:131], v[168:171], v[44:47]
	v_mfma_f32_16x16x32_bf16 v[40:43], v[136:139], v[168:171], v[40:43]
	v_mfma_f32_16x16x32_bf16 v[28:31], v[128:131], v[188:191], v[28:31]
	v_mfma_f32_16x16x32_bf16 v[24:27], v[136:139], v[188:191], v[24:27]
	v_mfma_f32_16x16x32_bf16 v[12:15], v[128:131], v[196:199], v[12:15]
	v_mfma_f32_16x16x32_bf16 v[8:11], v[136:139], v[196:199], v[8:11]
	v_mfma_f32_16x16x32_bf16 v[60:63], v[132:135], v[164:167], v[60:63]
	v_mfma_f32_16x16x32_bf16 v[56:59], v[140:143], v[164:167], v[56:59]
	v_mfma_f32_16x16x32_bf16 v[44:47], v[132:135], v[172:175], v[44:47]
	v_mfma_f32_16x16x32_bf16 v[40:43], v[140:143], v[172:175], v[40:43]
	v_mfma_f32_16x16x32_bf16 v[28:31], v[132:135], v[192:195], v[28:31]
	v_mfma_f32_16x16x32_bf16 v[24:27], v[140:143], v[192:195], v[24:27]
	v_mfma_f32_16x16x32_bf16 v[12:15], v[132:135], v[206:209], v[12:15]
	v_mfma_f32_16x16x32_bf16 v[8:11], v[140:143], v[206:209], v[8:11]
	v_mfma_f32_16x16x32_bf16 v[52:55], v[144:147], v[160:163], v[52:55]
	v_mfma_f32_16x16x32_bf16 v[48:51], v[152:155], v[160:163], v[48:51]
	v_mfma_f32_16x16x32_bf16 v[36:39], v[144:147], v[168:171], v[36:39]
	v_mfma_f32_16x16x32_bf16 v[32:35], v[152:155], v[168:171], v[32:35]
	v_mfma_f32_16x16x32_bf16 v[20:23], v[144:147], v[188:191], v[20:23]
	v_mfma_f32_16x16x32_bf16 v[16:19], v[152:155], v[188:191], v[16:19]
	v_mfma_f32_16x16x32_bf16 v[4:7], v[144:147], v[196:199], v[4:7]
	v_mfma_f32_16x16x32_bf16 v[0:3], v[152:155], v[196:199], v[0:3]
	v_mfma_f32_16x16x32_bf16 v[52:55], v[148:151], v[164:167], v[52:55]
	v_mfma_f32_16x16x32_bf16 v[48:51], v[156:159], v[164:167], v[48:51]
	v_mfma_f32_16x16x32_bf16 v[36:39], v[148:151], v[172:175], v[36:39]
	v_mfma_f32_16x16x32_bf16 v[32:35], v[156:159], v[172:175], v[32:35]
	v_mfma_f32_16x16x32_bf16 v[20:23], v[148:151], v[192:195], v[20:23]
	v_mfma_f32_16x16x32_bf16 v[16:19], v[156:159], v[192:195], v[16:19]
	v_mfma_f32_16x16x32_bf16 v[4:7], v[148:151], v[206:209], v[4:7]
	v_mfma_f32_16x16x32_bf16 v[0:3], v[156:159], v[206:209], v[0:3]
	s_setprio 0
	s_barrier
; #define PG8_STAGE(bufoff, gbase, voff) do { unsigned long long _gb = (unsigned long long)(gbase); asm volatile("" : "+s"(_gb)); _Pragma("unroll") for (int _i = 0; _i < 2; ++_i) \
;         __builtin_amdgcn_global_load_lds((const GAS unsigned*)((const GAS char*)_gb + (voff)[_i]), (LAS unsigned*)(lds + (bufoff) + ldsw + _i * 8192), 16, 0, 0); } while (0)
; #define PG8_LDA(dst, b, h) do { _Pragma("unroll") for (int m = 0; m < 4; ++m) _Pragma("unroll") for (int k = 0; k < 2; ++k) dst[m][k] = *(const LAS bf16x8*)(lds + PG8_SA(b, h) + aoff + m * 2048 + k * 1024); } while (0)
; #define PG8_LDB(dst, b, h) do { _Pragma("unroll") for (int n = 0; n < 2; ++n) _Pragma("unroll") for (int k = 0; k < 2; ++k) dst[n][k] = *(const LAS bf16x8*)(lds + PG8_SB(b, h) + boff + n * 2048 + k * 1024); } while (0)
; #define PG8_MMA(ai, bj, At, Bt) do { __builtin_amdgcn_s_setprio(1); _Pragma("unroll") for (int m = 0; m < 4; ++m) _Pragma("unroll") for (int n = 0; n < 2; ++n) _Pragma("unroll") for (int k = 0; k < 2; ++k) \
;         acc[ai][bj][m][n] = __builtin_amdgcn_mfma_f32_16x16x32_bf16(Bt[n][k], At[m][k], acc[ai][bj][m][n], 0, 0, 0); __builtin_amdgcn_s_setprio(0); } while (0)
; #define PG8_WAIT_V(n) asm volatile("s_waitcnt vmcnt(" #n ")" ::: "memory")
; #define PG8_WAIT_L(n) asm volatile("s_waitcnt lgkmcnt(" #n ")" ::: "memory")
; #define PG8_BAR __builtin_amdgcn_s_barrier()
; #define PG8_SCHED __builtin_amdgcn_sched_barrier(0)
; template <class Epi, bool ALIGN_EPI>
; __device__ __forceinline__ void gemm_phase(LAS unsigned char* lds, const Gemm g, const StaticOrder& S, const Epi& E, const int wid) {
;     ...
;             PG8_LDB(B0, 1, 0); PG8_LDB(B1, 1, 1); PG8_SCHED; PG8_LDA(At, 1, 0); PG8_STAGE(PG8_SA(0, 1), a2 + hstep, voffA);
;             PG8_WAIT_V(8); PG8_WAIT_L(0); PG8_BAR; PG8_MMA(0, 0, At, B0); PG8_MMA(0, 1, At, B1); PG8_BAR; PG8_SCHED;
;             PG8_LDA(At, 1, 1); PG8_STAGE(PG8_SB(1, 0), b3, voffB); PG8_STAGE(PG8_SB(1, 1), b3 + hstepB, voffB); PG8_STAGE(PG8_SA(1, 0), a3, voffA);
;             PG8_WAIT_V(8); PG8_WAIT_L(0); PG8_BAR; PG8_MMA(1, 0, At, B0); PG8_MMA(1, 1, At, B1); PG8_BAR; PG8_SCHED;
;         }
;         if constexpr (ALIGN_EPI) { if (wr == 0) PG8_BAR; }
	s_add_i32 s50, 0, 0x18000
	s_add_i32 s51, 0, 0x1c000
	v_add_u32_e32 v140, s50, v201
	v_add_u32_e32 v156, s51, v201
	ds_read_b128 v[128:131], v140
	ds_read_b128 v[132:135], v140 offset:1024
	ds_read_b128 v[136:139], v140 offset:2048
	ds_read_b128 v[140:143], v140 offset:3072
	ds_read_b128 v[144:147], v156
	ds_read_b128 v[148:151], v156 offset:1024
	ds_read_b128 v[152:155], v156 offset:2048
	ds_read_b128 v[156:159], v156 offset:3072
	s_add_u32 s24, s24, 0x80000
	s_addc_u32 s25, s25, 0
	s_mov_b32 m0, s30
	ds_read_b128 v[160:163], v204 offset:32768
	ds_read_b128 v[164:167], v204 offset:33792
	ds_read_b128 v[168:171], v204 offset:34816
	ds_read_b128 v[172:175], v204 offset:35840
	ds_read_b128 v[188:191], v204 offset:36864
	ds_read_b128 v[192:195], v204 offset:37888
	ds_read_b128 v[196:199], v204 offset:38912
	ds_read_b128 v[206:209], v204 offset:39936
	s_nop 0
	global_load_lds_dwordx4 v182, s[24:25]
	s_mov_b32 m0, s31
	s_nop 0
	global_load_lds_dwordx4 v178, s[24:25]
	s_waitcnt vmcnt(8) lgkmcnt(0)
	s_barrier
	s_setprio 1
	v_mfma_f32_16x16x32_bf16 v[124:127], v[128:131], v[160:163], v[124:127]
	v_mfma_f32_16x16x32_bf16 v[120:123], v[136:139], v[160:163], v[120:123]
	v_mfma_f32_16x16x32_bf16 v[108:111], v[128:131], v[168:171], v[108:111]
	v_mfma_f32_16x16x32_bf16 v[104:107], v[136:139], v[168:171], v[104:107]
	v_mfma_f32_16x16x32_bf16 v[92:95], v[128:131], v[188:191], v[92:95]
	v_mfma_f32_16x16x32_bf16 v[88:91], v[136:139], v[188:191], v[88:91]
	v_mfma_f32_16x16x32_bf16 v[76:79], v[128:131], v[196:199], v[76:79]
	v_mfma_f32_16x16x32_bf16 v[72:75], v[136:139], v[196:199], v[72:75]
	v_mfma_f32_16x16x32_bf16 v[124:127], v[132:135], v[164:167], v[124:127]
	v_mfma_f32_16x16x32_bf16 v[120:123], v[140:143], v[164:167], v[120:123]
	v_mfma_f32_16x16x32_bf16 v[108:111], v[132:135], v[172:175], v[108:111]
	v_mfma_f32_16x16x32_bf16 v[104:107], v[140:143], v[172:175], v[104:107]
	v_mfma_f32_16x16x32_bf16 v[92:95], v[132:135], v[192:195], v[92:95]
	v_mfma_f32_16x16x32_bf16 v[88:91], v[140:143], v[192:195], v[88:91]
	v_mfma_f32_16x16x32_bf16 v[76:79], v[132:135], v[206:209], v[76:79]
	v_mfma_f32_16x16x32_bf16 v[72:75], v[140:143], v[206:209], v[72:75]
	v_mfma_f32_16x16x32_bf16 v[116:119], v[144:147], v[160:163], v[116:119]
	v_mfma_f32_16x16x32_bf16 v[112:115], v[152:155], v[160:163], v[112:115]
	v_mfma_f32_16x16x32_bf16 v[100:103], v[144:147], v[168:171], v[100:103]
	v_mfma_f32_16x16x32_bf16 v[96:99], v[152:155], v[168:171], v[96:99]
	v_mfma_f32_16x16x32_bf16 v[84:87], v[144:147], v[188:191], v[84:87]
	v_mfma_f32_16x16x32_bf16 v[80:83], v[152:155], v[188:191], v[80:83]
	v_mfma_f32_16x16x32_bf16 v[68:71], v[144:147], v[196:199], v[68:71]
	v_mfma_f32_16x16x32_bf16 v[64:67], v[152:155], v[196:199], v[64:67]
	v_mfma_f32_16x16x32_bf16 v[116:119], v[148:151], v[164:167], v[116:119]
	v_mfma_f32_16x16x32_bf16 v[112:115], v[156:159], v[164:167], v[112:115]
	v_mfma_f32_16x16x32_bf16 v[100:103], v[148:151], v[172:175], v[100:103]
	v_mfma_f32_16x16x32_bf16 v[96:99], v[156:159], v[172:175], v[96:99]
	v_mfma_f32_16x16x32_bf16 v[84:87], v[148:151], v[192:195], v[84:87]
	v_mfma_f32_16x16x32_bf16 v[80:83], v[156:159], v[192:195], v[80:83]
	v_mfma_f32_16x16x32_bf16 v[68:71], v[148:151], v[206:209], v[68:71]
	v_mfma_f32_16x16x32_bf16 v[64:67], v[156:159], v[206:209], v[64:67]
	s_setprio 0
	s_barrier
	s_add_u32 s24, s22, 0x80
	s_addc_u32 s25, s23, 0
	s_add_i32 s50, s50, s33
	ds_read_b128 v[160:163], v204 offset:49152
	ds_read_b128 v[164:167], v204 offset:50176
	ds_read_b128 v[168:171], v204 offset:51200
	ds_read_b128 v[172:175], v204 offset:52224
	ds_read_b128 v[188:191], v204 offset:53248
	ds_read_b128 v[192:195], v204 offset:54272
	ds_read_b128 v[196:199], v204 offset:55296
	s_mov_b32 m0, s50
	ds_read_b128 v[206:209], v204 offset:56320
	global_load_lds_dwordx4 v180, s[24:25]
	s_add_i32 m0, s50, 0x2000
	s_add_u32 s22, s22, 0x20080
	s_addc_u32 s23, s23, 0
	global_load_lds_dwordx4 v176, s[24:25]
	s_add_i32 s24, s51, s33
	s_mov_b32 m0, s24
	s_nop 0
	global_load_lds_dwordx4 v180, s[22:23]
	s_add_i32 m0, s24, 0x2000
	s_nop 0
	global_load_lds_dwordx4 v176, s[22:23]
	s_mov_b32 m0, s34
	s_nop 0
	global_load_lds_dwordx4 v182, s[20:21]
	s_mov_b32 m0, s35
	s_nop 0
	global_load_lds_dwordx4 v178, s[20:21]
	s_waitcnt vmcnt(8) lgkmcnt(0)
	s_barrier
	s_setprio 1
	v_mfma_f32_16x16x32_bf16 v[60:63], v[128:131], v[160:163], v[60:63]
	v_mfma_f32_16x16x32_bf16 v[56:59], v[136:139], v[160:163], v[56:59]
	v_mfma_f32_16x16x32_bf16 v[44:47], v[128:131], v[168:171], v[44:47]
	v_mfma_f32_16x16x32_bf16 v[40:43], v[136:139], v[168:171], v[40:43]
	v_mfma_f32_16x16x32_bf16 v[28:31], v[128:131], v[188:191], v[28:31]
	v_mfma_f32_16x16x32_bf16 v[24:27], v[136:139], v[188:191], v[24:27]
	v_mfma_f32_16x16x32_bf16 v[12:15], v[128:131], v[196:199], v[12:15]
	v_mfma_f32_16x16x32_bf16 v[8:11], v[136:139], v[196:199], v[8:11]
	v_mfma_f32_16x16x32_bf16 v[60:63], v[132:135], v[164:167], v[60:63]
	v_mfma_f32_16x16x32_bf16 v[56:59], v[140:143], v[164:167], v[56:59]
	v_mfma_f32_16x16x32_bf16 v[44:47], v[132:135], v[172:175], v[44:47]
	v_mfma_f32_16x16x32_bf16 v[40:43], v[140:143], v[172:175], v[40:43]
	v_mfma_f32_16x16x32_bf16 v[28:31], v[132:135], v[192:195], v[28:31]
	v_mfma_f32_16x16x32_bf16 v[24:27], v[140:143], v[192:195], v[24:27]
	v_mfma_f32_16x16x32_bf16 v[12:15], v[132:135], v[206:209], v[12:15]
	v_mfma_f32_16x16x32_bf16 v[8:11], v[140:143], v[206:209], v[8:11]
	v_mfma_f32_16x16x32_bf16 v[52:55], v[144:147], v[160:163], v[52:55]
	v_mfma_f32_16x16x32_bf16 v[48:51], v[152:155], v[160:163], v[48:51]
	v_mfma_f32_16x16x32_bf16 v[36:39], v[144:147], v[168:171], v[36:39]
	v_mfma_f32_16x16x32_bf16 v[32:35], v[152:155], v[168:171], v[32:35]
	v_mfma_f32_16x16x32_bf16 v[20:23], v[144:147], v[188:191], v[20:23]
	v_mfma_f32_16x16x32_bf16 v[16:19], v[152:155], v[188:191], v[16:19]
	v_mfma_f32_16x16x32_bf16 v[4:7], v[144:147], v[196:199], v[4:7]
	v_mfma_f32_16x16x32_bf16 v[0:3], v[152:155], v[196:199], v[0:3]
	v_mfma_f32_16x16x32_bf16 v[52:55], v[148:151], v[164:167], v[52:55]
	v_mfma_f32_16x16x32_bf16 v[48:51], v[156:159], v[164:167], v[48:51]
	v_mfma_f32_16x16x32_bf16 v[36:39], v[148:151], v[172:175], v[36:39]
	v_mfma_f32_16x16x32_bf16 v[32:35], v[156:159], v[172:175], v[32:35]
	v_mfma_f32_16x16x32_bf16 v[20:23], v[148:151], v[192:195], v[20:23]
	v_mfma_f32_16x16x32_bf16 v[16:19], v[156:159], v[192:195], v[16:19]
	v_mfma_f32_16x16x32_bf16 v[4:7], v[148:151], v[206:209], v[4:7]
	v_mfma_f32_16x16x32_bf16 v[0:3], v[156:159], v[206:209], v[0:3]
	s_setprio 0
	s_barrier
	s_add_i32 s49, s49, 2
	s_add_u32 s45, s45, 0x100
	s_addc_u32 s46, s46, 0
	s_add_u32 s18, s18, 0x100
	s_addc_u32 s19, s19, 0
	s_add_u32 s47, s47, 0x100
	s_addc_u32 s48, s48, 0
	s_cmp_gt_u32 s49, 29
	s_cbranch_scc0 .LBB0_811
	s_and_b64 vcc, exec, s[84:85]
	s_cbranch_vccz .LBB0_814
	s_barrier
